# LN epilogues (P2,P7,P10): residual loads batched/prefetched instead of one serialized round trip per row group
# baseline (speedup 1.0000x reference)
;     __device__ __forceinline__ bool run(const f32x4 (&v)[2][2][4][2], const Unit& u, int wr, int wc, int fr, int fq, PG8_LAS unsigned char* lds, int wid, int lane) const {
;     ...
;                 s += __shfl_xor(s, 16); s += __shfl_xor(s, 32);
;     __device__ __forceinline__ void fused(f32x4 (&acc)[2][2][4][2], const Unit& u, int wr, int wc, int fr, int fq, PG8_LAS unsigned char* lds, int wid, int lane) const {
;     ...
;             for (int m = 0; m < 4; ++m) { const size_t off = (size_t)(u.pm * BM + ai * HALF + wr * 64 + m * 16 + fr) * ldc + col0;
; #pragma unroll
;                 for (int bj = 0; bj < 2; ++bj) { f32x4 b0, b1;
;                     if (base) { b0 = *(const f32x4*)(base + off + bj * HALF); b1 = *(const f32x4*)(base + off + bj * HALF + 4); }
;                     else { const u32x4 w = *(const u32x4*)(baseb + off + bj * HALF);
;                         b0 = (f32x4){__uint_as_float(w.x << 16), __uint_as_float(w.x & 0xffff0000u), __uint_as_float(w.y << 16), __uint_as_float(w.y & 0xffff0000u)};
;                         b1 = (f32x4){__uint_as_float(w.z << 16), __uint_as_float(w.z & 0xffff0000u), __uint_as_float(w.w << 16), __uint_as_float(w.w & 0xffff0000u)}; }
;                     acc[ai][bj][m][0] = acc[ai][bj][m][0] * s + b0 * alpha; acc[ai][bj][m][1] = acc[ai][bj][m][1] * s + b1 * alpha; }
.LBB0_194:
	s_lshl_b32 s0, s27, 5
	s_lshl_b32 s1, s60, 8
	v_lshrrev_b32_e32 v132, 1, v2
	s_or_b32 s0, s1, s0
	s_lshl_b32 s16, s25, 8
	v_and_or_b32 v164, v132, 24, s0
	s_add_i32 s0, s16, s36
	v_or_b32_e32 v134, s0, v152
	v_readlane_b32 s0, v245, 5
	v_readlane_b32 s4, v245, 9
	v_readlane_b32 s5, v245, 10
	v_readlane_b32 s6, v245, 11
	v_readlane_b32 s7, v245, 12
	v_readlane_b32 s8, v245, 13
	v_readlane_b32 s9, v245, 14
	v_readlane_b32 s10, v245, 15
	v_readlane_b32 s11, v245, 16
	v_readlane_b32 s12, v245, 17
	v_readlane_b32 s13, v245, 18
	v_readlane_b32 s14, v245, 19
	v_readlane_b32 s15, v245, 20
	v_ashrrev_i32_e32 v135, 31, v134
	v_readlane_b32 s1, v245, 6
	v_readlane_b32 s2, v245, 7
	v_readlane_b32 s3, v245, 8
	s_mov_b64 s[14:15], s[10:11]
	v_ashrrev_i32_e32 v165, 31, v164
	v_lshlrev_b64 v[132:133], 12, v[134:135]
	s_mov_b64 s[12:13], s[8:9]
	s_mov_b64 s[10:11], s[6:7]
	s_mov_b64 s[8:9], s[4:5]
	s_mov_b64 s[6:7], s[2:3]
	s_mov_b64 s[4:5], s[0:1]
	v_lshl_add_u64 v[136:137], s[4:5], 0, v[132:133]
	v_lshlrev_b64 v[132:133], 2, v[164:165]
	v_lshl_add_u64 v[148:149], v[136:137], 0, v[132:133]
	s_barrier
	s_nop 1
	v_subrev_u32_e32 v242, s4, v148
	global_load_dwordx4 v[176:179], v242, s[4:5]
	global_load_dwordx4 v[180:183], v242, s[4:5] offset:16
	global_load_dwordx4 v[184:187], v242, s[4:5] offset:512
	global_load_dwordx4 v[188:191], v242, s[4:5] offset:528
	s_add_u32 s100, s4, 0x10000
	s_addc_u32 s101, s5, 0
	global_load_dwordx4 v[192:195], v242, s[100:101]
	global_load_dwordx4 v[198:201], v242, s[100:101] offset:16
	global_load_dwordx4 v[202:205], v242, s[100:101] offset:512
	global_load_dwordx4 v[206:209], v242, s[100:101] offset:528
	s_add_u32 s98, s4, 0x20000
	s_addc_u32 s99, s5, 0
	global_load_dwordx4 v[210:213], v242, s[98:99]
	global_load_dwordx4 v[214:217], v242, s[98:99] offset:16
	global_load_dwordx4 v[218:221], v242, s[98:99] offset:512
	global_load_dwordx4 v[222:225], v242, s[98:99] offset:528
	s_add_u32 s100, s4, 0x30000
	s_addc_u32 s101, s5, 0
	global_load_dwordx4 v[226:229], v242, s[100:101]
	global_load_dwordx4 v[230:233], v242, s[100:101] offset:16
	global_load_dwordx4 v[246:249], v242, s[100:101] offset:512
	global_load_dwordx4 v[250:253], v242, s[100:101] offset:528
	s_nop 0
	v_or_b32_e32 v154, 16, v134
	v_ashrrev_i32_e32 v155, 31, v154
	s_mov_b32 s0, 0x3f9837f0
	v_lshlrev_b64 v[154:155], 12, v[154:155]
	v_lshl_add_u64 v[154:155], s[4:5], 0, v[154:155]
	v_lshl_add_u64 v[154:155], v[154:155], 0, v[132:133]
	v_mbcnt_lo_u32_b32 v135, -1, 0
	v_mbcnt_hi_u32_b32 v153, -1, v135
	v_and_b32_e32 v135, 64, v153
	v_add_u32_e32 v174, 64, v135
	s_waitcnt vmcnt(12)
	v_pk_mul_f32 v[138:139], v[178:179], s[0:1] op_sel_hi:[1,0]
	v_pk_mul_f32 v[136:137], v[176:177], s[0:1] op_sel_hi:[1,0]
	v_pk_mul_f32 v[142:143], v[182:183], s[0:1] op_sel_hi:[1,0]
	v_pk_mul_f32 v[140:141], v[180:181], s[0:1] op_sel_hi:[1,0]
	v_pk_mul_f32 v[146:147], v[186:187], s[0:1] op_sel_hi:[1,0]
	v_pk_mul_f32 v[144:145], v[184:185], s[0:1] op_sel_hi:[1,0]
	v_pk_mul_f32 v[150:151], v[190:191], s[0:1] op_sel_hi:[1,0]
	v_pk_mul_f32 v[148:149], v[188:189], s[0:1] op_sel_hi:[1,0]
	v_pk_fma_f32 v[114:115], v[114:115], 0.5, v[138:139] op_sel_hi:[1,0,1]
	v_pk_fma_f32 v[112:113], v[112:113], 0.5, v[136:137] op_sel_hi:[1,0,1]
	v_pk_fma_f32 v[126:127], v[126:127], 0.5, v[142:143] op_sel_hi:[1,0,1]
	v_pk_fma_f32 v[124:125], v[124:125], 0.5, v[140:141] op_sel_hi:[1,0,1]
	v_pk_fma_f32 v[110:111], v[110:111], 0.5, v[146:147] op_sel_hi:[1,0,1]
	v_pk_fma_f32 v[108:109], v[108:109], 0.5, v[144:145] op_sel_hi:[1,0,1]
	v_pk_fma_f32 v[94:95], v[94:95], 0.5, v[150:151] op_sel_hi:[1,0,1]
	v_pk_fma_f32 v[92:93], v[92:93], 0.5, v[148:149] op_sel_hi:[1,0,1]
	s_nop 0
	s_add_u32 s98, s4, 0x80000
	s_addc_u32 s99, s5, 0
	global_load_dwordx4 v[176:179], v242, s[98:99]
	global_load_dwordx4 v[180:183], v242, s[98:99] offset:16
	global_load_dwordx4 v[184:187], v242, s[98:99] offset:512
	global_load_dwordx4 v[188:191], v242, s[98:99] offset:528
	v_or_b32_e32 v154, 32, v134
	v_ashrrev_i32_e32 v155, 31, v154
	v_lshlrev_b64 v[154:155], 12, v[154:155]
	v_lshl_add_u64 v[154:155], s[4:5], 0, v[154:155]
	v_lshl_add_u64 v[154:155], v[154:155], 0, v[132:133]
	v_mov_b32_e32 v158, v113
	v_mov_b32_e32 v159, v114
	v_mov_b32_e32 v160, v112
	v_mov_b32_e32 v161, v115
	v_pk_add_f32 v[158:159], v[158:159], v[160:161]
	v_add_f32_e32 v163, v108, v109
	v_add_f32_e32 v167, v110, v111
	v_mov_b32_e32 v162, v92
	v_mov_b32_e32 v166, v93
	v_mov_b32_e32 v172, v95
	s_waitcnt vmcnt(15)
	v_pk_mul_f32 v[138:139], v[194:195], s[0:1] op_sel_hi:[1,0]
	v_pk_mul_f32 v[136:137], v[192:193], s[0:1] op_sel_hi:[1,0]
	s_waitcnt vmcnt(14)
	v_pk_mul_f32 v[142:143], v[200:201], s[0:1] op_sel_hi:[1,0]
	v_pk_mul_f32 v[140:141], v[198:199], s[0:1] op_sel_hi:[1,0]
	s_waitcnt vmcnt(13)
	v_pk_mul_f32 v[146:147], v[204:205], s[0:1] op_sel_hi:[1,0]
	v_pk_mul_f32 v[144:145], v[202:203], s[0:1] op_sel_hi:[1,0]
	s_waitcnt vmcnt(12)
	v_pk_mul_f32 v[150:151], v[208:209], s[0:1] op_sel_hi:[1,0]
	v_pk_mul_f32 v[148:149], v[206:207], s[0:1] op_sel_hi:[1,0]
	v_pk_fma_f32 v[98:99], v[98:99], 0.5, v[138:139] op_sel_hi:[1,0,1]
	v_pk_fma_f32 v[96:97], v[96:97], 0.5, v[136:137] op_sel_hi:[1,0,1]
	v_pk_fma_f32 v[130:131], v[130:131], 0.5, v[142:143] op_sel_hi:[1,0,1]
	v_pk_fma_f32 v[128:129], v[128:129], 0.5, v[140:141] op_sel_hi:[1,0,1]
	v_pk_fma_f32 v[82:83], v[82:83], 0.5, v[146:147] op_sel_hi:[1,0,1]
	v_pk_fma_f32 v[80:81], v[80:81], 0.5, v[144:145] op_sel_hi:[1,0,1]
	v_pk_fma_f32 v[70:71], v[70:71], 0.5, v[150:151] op_sel_hi:[1,0,1]
	v_pk_fma_f32 v[68:69], v[68:69], 0.5, v[148:149] op_sel_hi:[1,0,1]
	s_nop 0
	s_add_u32 s100, s4, 0x90000
	s_addc_u32 s101, s5, 0
	global_load_dwordx4 v[192:195], v242, s[100:101]
	global_load_dwordx4 v[198:201], v242, s[100:101] offset:16
	global_load_dwordx4 v[202:205], v242, s[100:101] offset:512
	global_load_dwordx4 v[206:209], v242, s[100:101] offset:528
	v_or_b32_e32 v154, 48, v134
	v_ashrrev_i32_e32 v155, 31, v154
	v_lshlrev_b64 v[154:155], 12, v[154:155]
	v_lshl_add_u64 v[154:155], s[4:5], 0, v[154:155]
	v_lshl_add_u64 v[154:155], v[154:155], 0, v[132:133]
	s_waitcnt vmcnt(15)
;     __device__ __forceinline__ void fused(f32x4 (&acc)[2][2][4][2], const Unit& u, int wr, int wc, int fr, int fq, PG8_LAS unsigned char* lds, int wid, int lane) const {
;     ...
;             for (int m = 0; m < 4; ++m) { const size_t off = (size_t)(u.pm * BM + ai * HALF + wr * 64 + m * 16 + fr) * ldc + col0;
; #pragma unroll
;                 for (int bj = 0; bj < 2; ++bj) { f32x4 b0, b1;
;                     if (base) { b0 = *(const f32x4*)(base + off + bj * HALF); b1 = *(const f32x4*)(base + off + bj * HALF + 4); }
;                     else { const u32x4 w = *(const u32x4*)(baseb + off + bj * HALF);
;                         b0 = (f32x4){__uint_as_float(w.x << 16), __uint_as_float(w.x & 0xffff0000u), __uint_as_float(w.y << 16), __uint_as_float(w.y & 0xffff0000u)};
;                         b1 = (f32x4){__uint_as_float(w.z << 16), __uint_as_float(w.z & 0xffff0000u), __uint_as_float(w.w << 16), __uint_as_float(w.w & 0xffff0000u)}; }
;                     acc[ai][bj][m][0] = acc[ai][bj][m][0] * s + b0 * alpha; acc[ai][bj][m][1] = acc[ai][bj][m][1] * s + b1 * alpha; }
	v_pk_mul_f32 v[138:139], v[212:213], s[0:1] op_sel_hi:[1,0]
	v_pk_mul_f32 v[136:137], v[210:211], s[0:1] op_sel_hi:[1,0]
	s_waitcnt vmcnt(14)
	v_pk_mul_f32 v[142:143], v[216:217], s[0:1] op_sel_hi:[1,0]
	v_pk_mul_f32 v[140:141], v[214:215], s[0:1] op_sel_hi:[1,0]
	s_waitcnt vmcnt(13)
	v_pk_mul_f32 v[146:147], v[220:221], s[0:1] op_sel_hi:[1,0]
	v_pk_mul_f32 v[144:145], v[218:219], s[0:1] op_sel_hi:[1,0]
	s_waitcnt vmcnt(12)
	v_pk_mul_f32 v[150:151], v[224:225], s[0:1] op_sel_hi:[1,0]
	v_pk_mul_f32 v[148:149], v[222:223], s[0:1] op_sel_hi:[1,0]
	v_pk_fma_f32 v[102:103], v[102:103], 0.5, v[138:139] op_sel_hi:[1,0,1]
	v_pk_fma_f32 v[100:101], v[100:101], 0.5, v[136:137] op_sel_hi:[1,0,1]
	v_pk_fma_f32 v[118:119], v[118:119], 0.5, v[142:143] op_sel_hi:[1,0,1]
	v_pk_fma_f32 v[116:117], v[116:117], 0.5, v[140:141] op_sel_hi:[1,0,1]
	v_pk_fma_f32 v[86:87], v[86:87], 0.5, v[146:147] op_sel_hi:[1,0,1]
	v_pk_fma_f32 v[84:85], v[84:85], 0.5, v[144:145] op_sel_hi:[1,0,1]
	v_pk_fma_f32 v[74:75], v[74:75], 0.5, v[150:151] op_sel_hi:[1,0,1]
	v_pk_fma_f32 v[72:73], v[72:73], 0.5, v[148:149] op_sel_hi:[1,0,1]
	s_nop 0
	s_add_u32 s98, s4, 0xa0000
	s_addc_u32 s99, s5, 0
	global_load_dwordx4 v[210:213], v242, s[98:99]
	global_load_dwordx4 v[214:217], v242, s[98:99] offset:16
	global_load_dwordx4 v[218:221], v242, s[98:99] offset:512
	global_load_dwordx4 v[222:225], v242, s[98:99] offset:528
	v_add_u32_e32 v154, 0x80, v134
	v_ashrrev_i32_e32 v155, 31, v154
	v_lshlrev_b64 v[154:155], 12, v[154:155]
	v_lshl_add_u64 v[154:155], s[4:5], 0, v[154:155]
	v_lshl_add_u64 v[154:155], v[154:155], 0, v[132:133]
	s_waitcnt vmcnt(15)
	v_pk_mul_f32 v[138:139], v[228:229], s[0:1] op_sel_hi:[1,0]
	v_pk_mul_f32 v[136:137], v[226:227], s[0:1] op_sel_hi:[1,0]
	s_waitcnt vmcnt(14)
	v_pk_mul_f32 v[142:143], v[232:233], s[0:1] op_sel_hi:[1,0]
	v_pk_mul_f32 v[140:141], v[230:231], s[0:1] op_sel_hi:[1,0]
	s_waitcnt vmcnt(13)
	v_pk_mul_f32 v[146:147], v[248:249], s[0:1] op_sel_hi:[1,0]
	v_pk_mul_f32 v[144:145], v[246:247], s[0:1] op_sel_hi:[1,0]
	s_waitcnt vmcnt(12)
	v_pk_mul_f32 v[150:151], v[252:253], s[0:1] op_sel_hi:[1,0]
	v_pk_mul_f32 v[148:149], v[250:251], s[0:1] op_sel_hi:[1,0]
	v_pk_fma_f32 v[106:107], v[106:107], 0.5, v[138:139] op_sel_hi:[1,0,1]
	v_pk_fma_f32 v[104:105], v[104:105], 0.5, v[136:137] op_sel_hi:[1,0,1]
	v_pk_fma_f32 v[122:123], v[122:123], 0.5, v[142:143] op_sel_hi:[1,0,1]
	v_pk_fma_f32 v[120:121], v[120:121], 0.5, v[140:141] op_sel_hi:[1,0,1]
	v_pk_fma_f32 v[90:91], v[90:91], 0.5, v[146:147] op_sel_hi:[1,0,1]
	v_pk_fma_f32 v[88:89], v[88:89], 0.5, v[144:145] op_sel_hi:[1,0,1]
	v_pk_fma_f32 v[78:79], v[78:79], 0.5, v[150:151] op_sel_hi:[1,0,1]
	v_pk_fma_f32 v[76:77], v[76:77], 0.5, v[148:149] op_sel_hi:[1,0,1]
	s_nop 0
	s_add_u32 s100, s4, 0xb0000
	s_addc_u32 s101, s5, 0
	global_load_dwordx4 v[226:229], v242, s[100:101] offset:16
	global_load_dwordx4 v[230:233], v242, s[100:101]
	global_load_dwordx4 v[246:249], v242, s[100:101] offset:528
	global_load_dwordx4 v[250:253], v242, s[100:101] offset:512
	v_add_u32_e32 v154, 0x90, v134
	v_ashrrev_i32_e32 v155, 31, v154
	v_lshlrev_b64 v[154:155], 12, v[154:155]
	v_lshl_add_u64 v[154:155], s[4:5], 0, v[154:155]
	v_lshl_add_u64 v[154:155], v[154:155], 0, v[132:133]
	s_waitcnt vmcnt(15)
	v_pk_mul_f32 v[138:139], v[178:179], s[0:1] op_sel_hi:[1,0]
	v_pk_mul_f32 v[136:137], v[176:177], s[0:1] op_sel_hi:[1,0]
	s_waitcnt vmcnt(14)
	v_pk_mul_f32 v[142:143], v[182:183], s[0:1] op_sel_hi:[1,0]
	v_pk_mul_f32 v[140:141], v[180:181], s[0:1] op_sel_hi:[1,0]
	s_waitcnt vmcnt(13)
	v_pk_mul_f32 v[146:147], v[186:187], s[0:1] op_sel_hi:[1,0]
	v_pk_mul_f32 v[144:145], v[184:185], s[0:1] op_sel_hi:[1,0]
	s_waitcnt vmcnt(12)
	v_pk_mul_f32 v[150:151], v[190:191], s[0:1] op_sel_hi:[1,0]
	v_pk_mul_f32 v[148:149], v[188:189], s[0:1] op_sel_hi:[1,0]
	v_pk_fma_f32 v[66:67], v[66:67], 0.5, v[138:139] op_sel_hi:[1,0,1]
	v_pk_fma_f32 v[64:65], v[64:65], 0.5, v[136:137] op_sel_hi:[1,0,1]
	v_pk_fma_f32 v[62:63], v[62:63], 0.5, v[142:143] op_sel_hi:[1,0,1]
	v_pk_fma_f32 v[60:61], v[60:61], 0.5, v[140:141] op_sel_hi:[1,0,1]
	v_pk_fma_f32 v[58:59], v[58:59], 0.5, v[146:147] op_sel_hi:[1,0,1]
	v_pk_fma_f32 v[56:57], v[56:57], 0.5, v[144:145] op_sel_hi:[1,0,1]
	v_pk_fma_f32 v[54:55], v[54:55], 0.5, v[150:151] op_sel_hi:[1,0,1]
	v_pk_fma_f32 v[52:53], v[52:53], 0.5, v[148:149] op_sel_hi:[1,0,1]
	s_nop 0
	v_add_u32_e32 v154, 0xa0, v134
	v_ashrrev_i32_e32 v155, 31, v154
	v_lshlrev_b64 v[154:155], 12, v[154:155]
	v_lshl_add_u64 v[154:155], s[4:5], 0, v[154:155]
	v_lshl_add_u64 v[154:155], v[154:155], 0, v[132:133]
	v_add_u32_e32 v134, 0xb0, v134
	v_ashrrev_i32_e32 v135, 31, v134
	s_waitcnt vmcnt(11)
	v_pk_mul_f32 v[138:139], v[194:195], s[0:1] op_sel_hi:[1,0]
	v_pk_mul_f32 v[136:137], v[192:193], s[0:1] op_sel_hi:[1,0]
	s_waitcnt vmcnt(10)
	v_pk_mul_f32 v[142:143], v[200:201], s[0:1] op_sel_hi:[1,0]
	v_pk_mul_f32 v[140:141], v[198:199], s[0:1] op_sel_hi:[1,0]
	s_waitcnt vmcnt(9)
	v_pk_mul_f32 v[146:147], v[204:205], s[0:1] op_sel_hi:[1,0]
	v_pk_mul_f32 v[144:145], v[202:203], s[0:1] op_sel_hi:[1,0]
	s_waitcnt vmcnt(8)
	v_pk_mul_f32 v[150:151], v[208:209], s[0:1] op_sel_hi:[1,0]
	v_pk_mul_f32 v[148:149], v[206:207], s[0:1] op_sel_hi:[1,0]
	v_pk_fma_f32 v[50:51], v[50:51], 0.5, v[138:139] op_sel_hi:[1,0,1]
	v_pk_fma_f32 v[48:49], v[48:49], 0.5, v[136:137] op_sel_hi:[1,0,1]
	v_pk_fma_f32 v[46:47], v[46:47], 0.5, v[142:143] op_sel_hi:[1,0,1]
	v_pk_fma_f32 v[44:45], v[44:45], 0.5, v[140:141] op_sel_hi:[1,0,1]
	v_pk_fma_f32 v[42:43], v[42:43], 0.5, v[146:147] op_sel_hi:[1,0,1]
	v_pk_fma_f32 v[40:41], v[40:41], 0.5, v[144:145] op_sel_hi:[1,0,1]
	v_pk_fma_f32 v[38:39], v[38:39], 0.5, v[150:151] op_sel_hi:[1,0,1]
	v_pk_fma_f32 v[36:37], v[36:37], 0.5, v[148:149] op_sel_hi:[1,0,1]
	s_nop 0
	v_xor_b32_e32 v154, 16, v153
	v_cmp_lt_i32_e32 vcc, v154, v174
	s_waitcnt vmcnt(7)
;     __device__ __forceinline__ bool run(const f32x4 (&v)[2][2][4][2], const Unit& u, int wr, int wc, int fr, int fq, PG8_LAS unsigned char* lds, int wid, int lane) const {
;     ...
;                 float s = 0.f;
; #pragma unroll
;                 for (int bj = 0; bj < 2; ++bj)
; #pragma unroll
;                     for (int n = 0; n < 2; ++n) { const f32x4 x = v[ai][bj][m][n]; s += (x[0] + x[1]) + (x[2] + x[3]); }
;                 s += __shfl_xor(s, 16); s += __shfl_xor(s, 32);
;                 const float mw = s * (1.0f / 64.0f); float q = 0.f;
; #pragma unroll
;                 for (int bj = 0; bj < 2; ++bj)
; #pragma unroll
;                     for (int n = 0; n < 2; ++n) { const f32x4 d = v[ai][bj][m][n] - mw; q += (d[0] * d[0] + d[1] * d[1]) + (d[2] * d[2] + d[3] * d[3]); }
;                 q += __shfl_xor(q, 16); q += __shfl_xor(q, 32);
;                 if (fq == 0) P[(ai * HALF + wr * 64 + m * 16 + fr) * 4 + wc] = (f32x2v){mw, q};
;     __device__ __forceinline__ void fused(f32x4 (&acc)[2][2][4][2], const Unit& u, int wr, int wc, int fr, int fq, PG8_LAS unsigned char* lds, int wid, int lane) const {
;     ...
;                 for (int bj = 0; bj < 2; ++bj) { f32x4 b0, b1;
;                     if (base) { b0 = *(const f32x4*)(base + off + bj * HALF); b1 = *(const f32x4*)(base + off + bj * HALF + 4); }
;                     else { const u32x4 w = *(const u32x4*)(baseb + off + bj * HALF);
;                         b0 = (f32x4){__uint_as_float(w.x << 16), __uint_as_float(w.x & 0xffff0000u), __uint_as_float(w.y << 16), __uint_as_float(w.y & 0xffff0000u)};
;                         b1 = (f32x4){__uint_as_float(w.z << 16), __uint_as_float(w.z & 0xffff0000u), __uint_as_float(w.w << 16), __uint_as_float(w.w & 0xffff0000u)}; }
;                     acc[ai][bj][m][0] = acc[ai][bj][m][0] * s + b0 * alpha; acc[ai][bj][m][1] = acc[ai][bj][m][1] * s + b1 * alpha; }
	v_pk_mul_f32 v[138:139], v[212:213], s[0:1] op_sel_hi:[1,0]
	v_cndmask_b32_e32 v156, v153, v154, vcc
	v_lshlrev_b64 v[154:155], 12, v[134:135]
	v_lshl_add_u64 v[154:155], s[4:5], 0, v[154:155]
	v_pk_mul_f32 v[136:137], v[210:211], s[0:1] op_sel_hi:[1,0]
	s_waitcnt vmcnt(6)
	v_pk_mul_f32 v[142:143], v[216:217], s[0:1] op_sel_hi:[1,0]
	v_pk_mul_f32 v[140:141], v[214:215], s[0:1] op_sel_hi:[1,0]
	s_waitcnt vmcnt(5)
	v_pk_mul_f32 v[146:147], v[220:221], s[0:1] op_sel_hi:[1,0]
	v_pk_mul_f32 v[144:145], v[218:219], s[0:1] op_sel_hi:[1,0]
	s_waitcnt vmcnt(4)
	v_pk_mul_f32 v[150:151], v[224:225], s[0:1] op_sel_hi:[1,0]
	v_pk_mul_f32 v[148:149], v[222:223], s[0:1] op_sel_hi:[1,0]
	v_lshl_add_u64 v[154:155], v[154:155], 0, v[132:133]
	v_pk_fma_f32 v[34:35], v[34:35], 0.5, v[138:139] op_sel_hi:[1,0,1]
	v_pk_fma_f32 v[32:33], v[32:33], 0.5, v[136:137] op_sel_hi:[1,0,1]
	v_pk_fma_f32 v[30:31], v[30:31], 0.5, v[142:143] op_sel_hi:[1,0,1]
	v_pk_fma_f32 v[28:29], v[28:29], 0.5, v[140:141] op_sel_hi:[1,0,1]
	v_pk_fma_f32 v[26:27], v[26:27], 0.5, v[146:147] op_sel_hi:[1,0,1]
	v_pk_fma_f32 v[24:25], v[24:25], 0.5, v[144:145] op_sel_hi:[1,0,1]
	v_pk_fma_f32 v[22:23], v[22:23], 0.5, v[150:151] op_sel_hi:[1,0,1]
	v_pk_fma_f32 v[20:21], v[20:21], 0.5, v[148:149] op_sel_hi:[1,0,1]
	v_lshlrev_b32_e32 v134, 2, v156
	s_nop 0
	v_mov_b32_e32 v136, v125
	v_mov_b32_e32 v137, v126
	v_mov_b32_e32 v138, v124
	v_mov_b32_e32 v139, v127
	v_pk_add_f32 v[136:137], v[136:137], v[138:139]
	v_add_f32_e32 v135, v158, v159
	v_pk_add_f32 v[136:137], v[136:137], v[136:137] op_sel_hi:[0,1]
	v_add_f32_e32 v173, 0, v135
	v_mov_b32_e32 v136, v94
	v_pk_add_f32 v[138:139], v[162:163], v[166:167]
	v_pk_add_f32 v[136:137], v[136:137], v[172:173]
	v_xor_b32_e32 v135, 32, v153
	v_pk_add_f32 v[136:137], v[138:139], v[136:137]
	v_cmp_lt_i32_e32 vcc, v135, v174
	v_add_f32_e32 v136, v136, v137
	ds_bpermute_b32 v137, v134, v136
	v_cndmask_b32_e32 v135, v153, v135, vcc
	v_lshlrev_b32_e32 v135, 2, v135
	s_waitcnt lgkmcnt(0)
	v_add_f32_e32 v136, v136, v137
	ds_bpermute_b32 v137, v135, v136
	s_waitcnt lgkmcnt(0)
	v_add_f32_e32 v137, v136, v137
	v_fmamk_f32 v138, v137, 0xbc800000, v115
	v_fmamk_f32 v153, v137, 0xbc800000, v113
	v_fmamk_f32 v159, v137, 0xbc800000, v127
	v_fmamk_f32 v161, v137, 0xbc800000, v125
	v_fmamk_f32 v136, v137, 0xbc800000, v114
	v_fmamk_f32 v139, v137, 0xbc800000, v112
	v_fmamk_f32 v158, v137, 0xbc800000, v126
	v_fmamk_f32 v160, v137, 0xbc800000, v124
	v_fmamk_f32 v163, v137, 0xbc800000, v111
	v_fmamk_f32 v167, v137, 0xbc800000, v109
	v_mul_f32_e32 v153, v153, v153
	v_mul_f32_e32 v138, v138, v138
	v_mul_f32_e32 v161, v161, v161
	v_mul_f32_e32 v159, v159, v159
	v_fmamk_f32 v162, v137, 0xbc800000, v110
	v_fmamk_f32 v166, v137, 0xbc800000, v108
	v_fmamk_f32 v173, v137, 0xbc800000, v95
	v_fmamk_f32 v175, v137, 0xbc800000, v93
	v_mul_f32_e32 v167, v167, v167
	v_mul_f32_e32 v163, v163, v163
	v_fmac_f32_e32 v153, v139, v139
	v_fmac_f32_e32 v138, v136, v136
	v_fmac_f32_e32 v161, v160, v160
	v_fmac_f32_e32 v159, v158, v158
	v_fmamk_f32 v172, v137, 0xbc800000, v94
	v_fmamk_f32 v174, v137, 0xbc800000, v92
	v_mul_f32_e32 v175, v175, v175
	v_mul_f32_e32 v173, v173, v173
	v_fmac_f32_e32 v167, v166, v166
	v_fmac_f32_e32 v163, v162, v162
	v_add_f32_e32 v136, v153, v138
	v_add_f32_e32 v138, v161, v159
	v_fmac_f32_e32 v175, v174, v174
	v_fmac_f32_e32 v173, v172, v172
	v_add_f32_e32 v139, v167, v163
	v_add_f32_e32 v136, v136, v138
	v_add_f32_e32 v153, v175, v173
	v_add_f32_e32 v136, v139, v136
	v_add_f32_e32 v138, v153, v136
	ds_bpermute_b32 v139, v134, v138
	v_and_b32_e32 v136, 63, v2
	v_cmp_gt_u32_e32 vcc, 16, v136
	s_waitcnt lgkmcnt(0)
	v_add_f32_e32 v138, v138, v139
	ds_bpermute_b32 v139, v135, v138
	s_waitcnt vmcnt(3)
	v_pk_mul_f32 v[142:143], v[228:229], s[0:1] op_sel_hi:[1,0]
	s_waitcnt vmcnt(2)
	v_pk_mul_f32 v[146:147], v[232:233], s[0:1] op_sel_hi:[1,0]
	v_pk_mul_f32 v[144:145], v[230:231], s[0:1] op_sel_hi:[1,0]
	v_pk_mul_f32 v[140:141], v[226:227], s[0:1] op_sel_hi:[1,0]
	s_waitcnt vmcnt(0)
	v_pk_mul_f32 v[156:157], v[252:253], s[0:1] op_sel_hi:[1,0]
	v_pk_mul_f32 v[154:155], v[250:251], s[0:1] op_sel_hi:[1,0]
	v_pk_mul_f32 v[150:151], v[248:249], s[0:1] op_sel_hi:[1,0]
	v_pk_mul_f32 v[148:149], v[246:247], s[0:1] op_sel_hi:[1,0]
	v_pk_fma_f32 v[18:19], v[18:19], 0.5, v[146:147] op_sel_hi:[1,0,1]
	v_pk_fma_f32 v[16:17], v[16:17], 0.5, v[144:145] op_sel_hi:[1,0,1]
	v_pk_fma_f32 v[14:15], v[14:15], 0.5, v[142:143] op_sel_hi:[1,0,1]
	v_pk_fma_f32 v[12:13], v[12:13], 0.5, v[140:141] op_sel_hi:[1,0,1]
	v_pk_fma_f32 v[10:11], v[10:11], 0.5, v[156:157] op_sel_hi:[1,0,1]
	v_pk_fma_f32 v[8:9], v[8:9], 0.5, v[154:155] op_sel_hi:[1,0,1]
	v_pk_fma_f32 v[6:7], v[6:7], 0.5, v[150:151] op_sel_hi:[1,0,1]
	v_pk_fma_f32 v[4:5], v[4:5], 0.5, v[148:149] op_sel_hi:[1,0,1]
	s_lshl_b32 s0, s27, 3
	s_add_i32 s2, s0, 0
	s_and_saveexec_b64 s[0:1], vcc
	s_cbranch_execz .LBB0_196
	s_lshl_b32 s3, s26, 11
	s_add_i32 s3, s2, s3
	v_mul_f32_e32 v140, 0x3c800000, v137
	v_lshl_add_u32 v137, v152, 5, s3
	s_waitcnt lgkmcnt(0)
	v_add_f32_e32 v141, v138, v139
	ds_write_b64 v137, v[140:141]

;     __device__ __forceinline__ void fused(f32x4 (&acc)[2][2][4][2], const Unit& u, int wr, int wc, int fr, int fq, PG8_LAS unsigned char* lds, int wid, int lane) const {
;     ...
;             for (int m = 0; m < 4; ++m) { const size_t off = (size_t)(u.pm * BM + ai * HALF + wr * 64 + m * 16 + fr) * ldc + col0;
; #pragma unroll
;                 for (int bj = 0; bj < 2; ++bj) { f32x4 b0, b1;
;                     if (base) { b0 = *(const f32x4*)(base + off + bj * HALF); b1 = *(const f32x4*)(base + off + bj * HALF + 4); }
;                     else { const u32x4 w = *(const u32x4*)(baseb + off + bj * HALF);
;                         b0 = (f32x4){__uint_as_float(w.x << 16), __uint_as_float(w.x & 0xffff0000u), __uint_as_float(w.y << 16), __uint_as_float(w.y & 0xffff0000u)};
;                         b1 = (f32x4){__uint_as_float(w.z << 16), __uint_as_float(w.z & 0xffff0000u), __uint_as_float(w.w << 16), __uint_as_float(w.w & 0xffff0000u)}; }
;                     acc[ai][bj][m][0] = acc[ai][bj][m][0] * s + b0 * alpha; acc[ai][bj][m][1] = acc[ai][bj][m][1] * s + b1 * alpha; }
.LBB0_1496:
	s_lshl_b32 s0, s13, 5
	s_lshl_b32 s1, s20, 8
	v_lshrrev_b32_e32 v130, 1, v150
	s_or_b32 s0, s1, s0
	s_lshl_b32 s22, s12, 8
	v_and_or_b32 v130, v130, 24, s0
	s_add_i32 s0, s22, s35
	v_or_b32_e32 v132, s0, v151
	v_ashrrev_i32_e32 v133, 31, v132
	v_readlane_b32 s2, v245, 57
	v_ashrrev_i32_e32 v131, 31, v130
	v_lshlrev_b64 v[134:135], 11, v[132:133]
	v_readlane_b32 s3, v245, 58
	v_lshlrev_b64 v[162:163], 1, v[130:131]
	s_barrier
	v_lshl_add_u64 v[134:135], s[2:3], 0, v[134:135]
	v_lshl_add_u64 v[138:139], v[134:135], 0, v[162:163]
	s_nop 1
	v_subrev_u32_e32 v175, s2, v138
	global_load_dwordx4 v[176:179], v175, s[2:3]
	global_load_dwordx4 v[180:183], v175, s[2:3] offset:256
	s_add_u32 s100, s2, 0x8000
	s_addc_u32 s101, s3, 0
	global_load_dwordx4 v[184:187], v175, s[100:101]
	global_load_dwordx4 v[188:191], v175, s[100:101] offset:256
	s_add_u32 s98, s2, 0x10000
	s_addc_u32 s99, s3, 0
	global_load_dwordx4 v[192:195], v175, s[98:99]
	global_load_dwordx4 v[196:199], v175, s[98:99] offset:256
	s_add_u32 s100, s2, 0x18000
	s_addc_u32 s101, s3, 0
	global_load_dwordx4 v[200:203], v175, s[100:101]
	global_load_dwordx4 v[204:207], v175, s[100:101] offset:256
	s_add_u32 s98, s2, 0x40000
	s_addc_u32 s99, s3, 0
	global_load_dwordx4 v[208:211], v175, s[98:99]
	global_load_dwordx4 v[212:215], v175, s[98:99] offset:256
	s_add_u32 s100, s2, 0x48000
	s_addc_u32 s101, s3, 0
	global_load_dwordx4 v[216:219], v175, s[100:101]
	global_load_dwordx4 v[220:223], v175, s[100:101] offset:256
	s_add_u32 s98, s2, 0x50000
	s_addc_u32 s99, s3, 0
	global_load_dwordx4 v[224:227], v175, s[98:99]
	global_load_dwordx4 v[228:231], v175, s[98:99] offset:256
	s_add_u32 s100, s2, 0x58000
	s_addc_u32 s101, s3, 0
	global_load_dwordx4 v[232:235], v175, s[100:101]
	global_load_dwordx4 v[236:239], v175, s[100:101] offset:256
	s_nop 0
	v_or_b32_e32 v142, 16, v132
	v_ashrrev_i32_e32 v143, 31, v142
	v_lshlrev_b64 v[142:143], 11, v[142:143]
	s_mov_b32 s0, 0x3f9837f0
	v_lshl_add_u64 v[142:143], s[2:3], 0, v[142:143]
	v_lshl_add_u64 v[142:143], v[142:143], 0, v[162:163]
	v_mbcnt_hi_u32_b32 v133, -1, v1
	s_waitcnt vmcnt(14)
	v_lshlrev_b32_e32 v144, 16, v176
	v_and_b32_e32 v145, 0xffff0000, v176
	v_lshlrev_b32_e32 v134, 16, v177
	v_and_b32_e32 v135, 0xffff0000, v177
	v_lshlrev_b32_e32 v146, 16, v178
	v_and_b32_e32 v147, 0xffff0000, v178
	v_lshlrev_b32_e32 v136, 16, v179
	v_and_b32_e32 v137, 0xffff0000, v179
	v_lshlrev_b32_e32 v148, 16, v180
	v_and_b32_e32 v149, 0xffff0000, v180
	v_lshlrev_b32_e32 v138, 16, v181
	v_and_b32_e32 v139, 0xffff0000, v181
	v_lshlrev_b32_e32 v152, 16, v182
	v_and_b32_e32 v153, 0xffff0000, v182
	v_lshlrev_b32_e32 v140, 16, v183
	v_and_b32_e32 v141, 0xffff0000, v183
	v_pk_fma_f32 v[96:97], v[134:135], s[0:1], v[96:97] op_sel_hi:[1,0,1]
	v_pk_fma_f32 v[94:95], v[144:145], s[0:1], v[94:95] op_sel_hi:[1,0,1]
	v_pk_fma_f32 v[104:105], v[136:137], s[0:1], v[104:105] op_sel_hi:[1,0,1]
	v_pk_fma_f32 v[102:103], v[146:147], s[0:1], v[102:103] op_sel_hi:[1,0,1]
	v_pk_fma_f32 v[92:93], v[138:139], s[0:1], v[92:93] op_sel_hi:[1,0,1]
	v_pk_fma_f32 v[90:91], v[148:149], s[0:1], v[90:91] op_sel_hi:[1,0,1]
	v_pk_fma_f32 v[76:77], v[140:141], s[0:1], v[76:77] op_sel_hi:[1,0,1]
	v_pk_fma_f32 v[74:75], v[152:153], s[0:1], v[74:75] op_sel_hi:[1,0,1]
	s_nop 0
	v_or_b32_e32 v142, 32, v132
	v_ashrrev_i32_e32 v143, 31, v142
	v_lshlrev_b64 v[142:143], 11, v[142:143]
	v_lshl_add_u64 v[142:143], s[2:3], 0, v[142:143]
	v_lshl_add_u64 v[142:143], v[142:143], 0, v[162:163]
	s_waitcnt vmcnt(13)
	v_lshlrev_b32_e32 v144, 16, v184
	v_and_b32_e32 v145, 0xffff0000, v184
	v_lshlrev_b32_e32 v134, 16, v185
	v_and_b32_e32 v135, 0xffff0000, v185
	v_lshlrev_b32_e32 v146, 16, v186
	v_and_b32_e32 v147, 0xffff0000, v186
	v_lshlrev_b32_e32 v136, 16, v187
	v_and_b32_e32 v137, 0xffff0000, v187
	s_waitcnt vmcnt(12)
	v_lshlrev_b32_e32 v148, 16, v188
	v_and_b32_e32 v149, 0xffff0000, v188
	v_lshlrev_b32_e32 v138, 16, v189
	v_and_b32_e32 v139, 0xffff0000, v189
	v_lshlrev_b32_e32 v152, 16, v190
	v_and_b32_e32 v153, 0xffff0000, v190
	v_lshlrev_b32_e32 v140, 16, v191
	v_and_b32_e32 v141, 0xffff0000, v191
	v_pk_fma_f32 v[108:109], v[134:135], s[0:1], v[108:109] op_sel_hi:[1,0,1]
	v_pk_fma_f32 v[106:107], v[144:145], s[0:1], v[106:107] op_sel_hi:[1,0,1]
	v_pk_fma_f32 v[112:113], v[136:137], s[0:1], v[112:113] op_sel_hi:[1,0,1]
	v_pk_fma_f32 v[110:111], v[146:147], s[0:1], v[110:111] op_sel_hi:[1,0,1]
	v_pk_fma_f32 v[80:81], v[138:139], s[0:1], v[80:81] op_sel_hi:[1,0,1]
	v_pk_fma_f32 v[78:79], v[148:149], s[0:1], v[78:79] op_sel_hi:[1,0,1]
	v_pk_fma_f32 v[68:69], v[140:141], s[0:1], v[68:69] op_sel_hi:[1,0,1]
	v_pk_fma_f32 v[66:67], v[152:153], s[0:1], v[66:67] op_sel_hi:[1,0,1]
	s_nop 0
	v_or_b32_e32 v142, 48, v132
	v_ashrrev_i32_e32 v143, 31, v142
	v_lshlrev_b64 v[142:143], 11, v[142:143]
	v_lshl_add_u64 v[142:143], s[2:3], 0, v[142:143]
	v_lshl_add_u64 v[142:143], v[142:143], 0, v[162:163]
	s_waitcnt vmcnt(11)
	v_lshlrev_b32_e32 v144, 16, v192
	v_and_b32_e32 v145, 0xffff0000, v192
	v_lshlrev_b32_e32 v134, 16, v193
	v_and_b32_e32 v135, 0xffff0000, v193
	v_lshlrev_b32_e32 v146, 16, v194
	v_and_b32_e32 v147, 0xffff0000, v194
	v_lshlrev_b32_e32 v136, 16, v195
	v_and_b32_e32 v137, 0xffff0000, v195
	s_waitcnt vmcnt(10)
;     __device__ __forceinline__ void fused(f32x4 (&acc)[2][2][4][2], const Unit& u, int wr, int wc, int fr, int fq, PG8_LAS unsigned char* lds, int wid, int lane) const {
;     ...
;             for (int m = 0; m < 4; ++m) { const size_t off = (size_t)(u.pm * BM + ai * HALF + wr * 64 + m * 16 + fr) * ldc + col0;
; #pragma unroll
;                 for (int bj = 0; bj < 2; ++bj) { f32x4 b0, b1;
;                     if (base) { b0 = *(const f32x4*)(base + off + bj * HALF); b1 = *(const f32x4*)(base + off + bj * HALF + 4); }
;                     else { const u32x4 w = *(const u32x4*)(baseb + off + bj * HALF);
;                         b0 = (f32x4){__uint_as_float(w.x << 16), __uint_as_float(w.x & 0xffff0000u), __uint_as_float(w.y << 16), __uint_as_float(w.y & 0xffff0000u)};
;                         b1 = (f32x4){__uint_as_float(w.z << 16), __uint_as_float(w.z & 0xffff0000u), __uint_as_float(w.w << 16), __uint_as_float(w.w & 0xffff0000u)}; }
;                     acc[ai][bj][m][0] = acc[ai][bj][m][0] * s + b0 * alpha; acc[ai][bj][m][1] = acc[ai][bj][m][1] * s + b1 * alpha; }
	v_lshlrev_b32_e32 v148, 16, v196
	v_and_b32_e32 v149, 0xffff0000, v196
	v_lshlrev_b32_e32 v138, 16, v197
	v_and_b32_e32 v139, 0xffff0000, v197
	v_lshlrev_b32_e32 v152, 16, v198
	v_and_b32_e32 v153, 0xffff0000, v198
	v_lshlrev_b32_e32 v140, 16, v199
	v_and_b32_e32 v141, 0xffff0000, v199
	v_pk_fma_f32 v[116:117], v[134:135], s[0:1], v[116:117] op_sel_hi:[1,0,1]
	v_pk_fma_f32 v[114:115], v[144:145], s[0:1], v[114:115] op_sel_hi:[1,0,1]
	v_pk_fma_f32 v[124:125], v[136:137], s[0:1], v[124:125] op_sel_hi:[1,0,1]
	v_pk_fma_f32 v[122:123], v[146:147], s[0:1], v[122:123] op_sel_hi:[1,0,1]
	v_pk_fma_f32 v[100:101], v[138:139], s[0:1], v[100:101] op_sel_hi:[1,0,1]
	v_pk_fma_f32 v[98:99], v[148:149], s[0:1], v[98:99] op_sel_hi:[1,0,1]
	v_pk_fma_f32 v[88:89], v[140:141], s[0:1], v[88:89] op_sel_hi:[1,0,1]
	v_pk_fma_f32 v[86:87], v[152:153], s[0:1], v[86:87] op_sel_hi:[1,0,1]
	s_nop 0
	v_add_u32_e32 v142, 0x80, v132
	v_ashrrev_i32_e32 v143, 31, v142
	v_lshlrev_b64 v[142:143], 11, v[142:143]
	v_lshl_add_u64 v[142:143], s[2:3], 0, v[142:143]
	v_lshl_add_u64 v[142:143], v[142:143], 0, v[162:163]
	s_waitcnt vmcnt(9)
	v_lshlrev_b32_e32 v144, 16, v200
	v_and_b32_e32 v145, 0xffff0000, v200
	v_lshlrev_b32_e32 v134, 16, v201
	v_and_b32_e32 v135, 0xffff0000, v201
	v_lshlrev_b32_e32 v146, 16, v202
	v_and_b32_e32 v147, 0xffff0000, v202
	v_lshlrev_b32_e32 v136, 16, v203
	v_and_b32_e32 v137, 0xffff0000, v203
	s_waitcnt vmcnt(8)
	v_lshlrev_b32_e32 v148, 16, v204
	v_and_b32_e32 v149, 0xffff0000, v204
	v_lshlrev_b32_e32 v138, 16, v205
	v_and_b32_e32 v139, 0xffff0000, v205
	v_lshlrev_b32_e32 v152, 16, v206
	v_and_b32_e32 v153, 0xffff0000, v206
	v_lshlrev_b32_e32 v140, 16, v207
	v_and_b32_e32 v141, 0xffff0000, v207
	v_pk_fma_f32 v[128:129], v[134:135], s[0:1], v[128:129] op_sel_hi:[1,0,1]
	v_pk_fma_f32 v[126:127], v[144:145], s[0:1], v[126:127] op_sel_hi:[1,0,1]
	v_pk_fma_f32 v[120:121], v[136:137], s[0:1], v[120:121] op_sel_hi:[1,0,1]
	v_pk_fma_f32 v[118:119], v[146:147], s[0:1], v[118:119] op_sel_hi:[1,0,1]
	v_pk_fma_f32 v[84:85], v[138:139], s[0:1], v[84:85] op_sel_hi:[1,0,1]
	v_pk_fma_f32 v[82:83], v[148:149], s[0:1], v[82:83] op_sel_hi:[1,0,1]
	v_pk_fma_f32 v[72:73], v[140:141], s[0:1], v[72:73] op_sel_hi:[1,0,1]
	v_pk_fma_f32 v[70:71], v[152:153], s[0:1], v[70:71] op_sel_hi:[1,0,1]
	s_nop 0
	v_add_u32_e32 v142, 0x90, v132
	v_ashrrev_i32_e32 v143, 31, v142
	v_lshlrev_b64 v[142:143], 11, v[142:143]
	v_lshl_add_u64 v[142:143], s[2:3], 0, v[142:143]
	v_lshl_add_u64 v[142:143], v[142:143], 0, v[162:163]
	s_waitcnt vmcnt(7)
	v_lshlrev_b32_e32 v144, 16, v208
	v_and_b32_e32 v145, 0xffff0000, v208
	v_lshlrev_b32_e32 v134, 16, v209
	v_and_b32_e32 v135, 0xffff0000, v209
	v_lshlrev_b32_e32 v146, 16, v210
	v_and_b32_e32 v147, 0xffff0000, v210
	v_lshlrev_b32_e32 v136, 16, v211
	v_and_b32_e32 v137, 0xffff0000, v211
	s_waitcnt vmcnt(6)
	v_lshlrev_b32_e32 v148, 16, v212
	v_and_b32_e32 v149, 0xffff0000, v212
	v_lshlrev_b32_e32 v138, 16, v213
	v_and_b32_e32 v139, 0xffff0000, v213
	v_lshlrev_b32_e32 v152, 16, v214
	v_and_b32_e32 v153, 0xffff0000, v214
	v_lshlrev_b32_e32 v140, 16, v215
	v_and_b32_e32 v141, 0xffff0000, v215
	v_pk_fma_f32 v[64:65], v[134:135], s[0:1], v[64:65] op_sel_hi:[1,0,1]
	v_pk_fma_f32 v[62:63], v[144:145], s[0:1], v[62:63] op_sel_hi:[1,0,1]
	v_pk_fma_f32 v[60:61], v[136:137], s[0:1], v[60:61] op_sel_hi:[1,0,1]
	v_pk_fma_f32 v[58:59], v[146:147], s[0:1], v[58:59] op_sel_hi:[1,0,1]
	v_pk_fma_f32 v[56:57], v[138:139], s[0:1], v[56:57] op_sel_hi:[1,0,1]
	v_pk_fma_f32 v[54:55], v[148:149], s[0:1], v[54:55] op_sel_hi:[1,0,1]
	v_pk_fma_f32 v[52:53], v[140:141], s[0:1], v[52:53] op_sel_hi:[1,0,1]
	v_pk_fma_f32 v[50:51], v[152:153], s[0:1], v[50:51] op_sel_hi:[1,0,1]
	s_nop 0
	v_add_u32_e32 v142, 0xa0, v132
	v_ashrrev_i32_e32 v143, 31, v142
	v_lshlrev_b64 v[142:143], 11, v[142:143]
	v_lshl_add_u64 v[142:143], s[2:3], 0, v[142:143]
	v_lshl_add_u64 v[142:143], v[142:143], 0, v[162:163]
	s_waitcnt vmcnt(5)
	v_lshlrev_b32_e32 v144, 16, v216
	v_and_b32_e32 v145, 0xffff0000, v216
	v_lshlrev_b32_e32 v134, 16, v217
	v_and_b32_e32 v135, 0xffff0000, v217
	v_lshlrev_b32_e32 v146, 16, v218
	v_and_b32_e32 v147, 0xffff0000, v218
	v_lshlrev_b32_e32 v136, 16, v219
	v_and_b32_e32 v137, 0xffff0000, v219
	s_waitcnt vmcnt(4)
	v_lshlrev_b32_e32 v148, 16, v220
	v_and_b32_e32 v149, 0xffff0000, v220
	v_lshlrev_b32_e32 v138, 16, v221
	v_and_b32_e32 v139, 0xffff0000, v221
	v_lshlrev_b32_e32 v152, 16, v222
	v_and_b32_e32 v153, 0xffff0000, v222
	v_lshlrev_b32_e32 v140, 16, v223
	v_and_b32_e32 v141, 0xffff0000, v223
	v_pk_fma_f32 v[48:49], v[134:135], s[0:1], v[48:49] op_sel_hi:[1,0,1]
	v_pk_fma_f32 v[46:47], v[144:145], s[0:1], v[46:47] op_sel_hi:[1,0,1]
	v_pk_fma_f32 v[44:45], v[136:137], s[0:1], v[44:45] op_sel_hi:[1,0,1]
	v_pk_fma_f32 v[42:43], v[146:147], s[0:1], v[42:43] op_sel_hi:[1,0,1]
	v_pk_fma_f32 v[40:41], v[138:139], s[0:1], v[40:41] op_sel_hi:[1,0,1]
	v_pk_fma_f32 v[38:39], v[148:149], s[0:1], v[38:39] op_sel_hi:[1,0,1]
	v_pk_fma_f32 v[36:37], v[140:141], s[0:1], v[36:37] op_sel_hi:[1,0,1]
	v_pk_fma_f32 v[34:35], v[152:153], s[0:1], v[34:35] op_sel_hi:[1,0,1]
	v_mov_b32_e32 v146, v95
	v_and_b32_e32 v142, 64, v133
	v_xor_b32_e32 v143, 16, v133
	v_add_u32_e32 v158, 64, v142
	v_add_u32_e32 v142, 0xb0, v132
	v_cmp_lt_i32_e32 vcc, v143, v158
	v_mov_b32_e32 v147, v96
	v_mov_b32_e32 v148, v94
	v_cndmask_b32_e32 v132, v133, v143, vcc
	v_ashrrev_i32_e32 v143, 31, v142
	v_lshlrev_b64 v[142:143], 11, v[142:143]
	v_lshl_add_u64 v[142:143], s[2:3], 0, v[142:143]
	v_lshl_add_u64 v[142:143], v[142:143], 0, v[162:163]
	v_mov_b32_e32 v149, v97
	v_pk_add_f32 v[146:147], v[146:147], v[148:149]
	v_lshlrev_b32_e32 v132, 2, v132
	v_add_f32_e32 v146, v146, v147
	s_waitcnt vmcnt(3)
;     __device__ __forceinline__ bool run(const f32x4 (&v)[2][2][4][2], const Unit& u, int wr, int wc, int fr, int fq, PG8_LAS unsigned char* lds, int wid, int lane) const {
;     ...
;                 float s = 0.f;
; #pragma unroll
;                 for (int bj = 0; bj < 2; ++bj)
; #pragma unroll
;                     for (int n = 0; n < 2; ++n) { const f32x4 x = v[ai][bj][m][n]; s += (x[0] + x[1]) + (x[2] + x[3]); }
;                 s += __shfl_xor(s, 16); s += __shfl_xor(s, 32);
;                 const float mw = s * (1.0f / 64.0f); float q = 0.f;
; #pragma unroll
;                 for (int bj = 0; bj < 2; ++bj)
; #pragma unroll
;                     for (int n = 0; n < 2; ++n) { const f32x4 d = v[ai][bj][m][n] - mw; q += (d[0] * d[0] + d[1] * d[1]) + (d[2] * d[2] + d[3] * d[3]); }
;                 q += __shfl_xor(q, 16); q += __shfl_xor(q, 32);
;                 if (fq == 0) P[(ai * HALF + wr * 64 + m * 16 + fr) * 4 + wc] = (f32x2v){mw, q};
;     __device__ __forceinline__ void fused(f32x4 (&acc)[2][2][4][2], const Unit& u, int wr, int wc, int fr, int fq, PG8_LAS unsigned char* lds, int wid, int lane) const {
;     ...
;                 for (int bj = 0; bj < 2; ++bj) { f32x4 b0, b1;
;                     if (base) { b0 = *(const f32x4*)(base + off + bj * HALF); b1 = *(const f32x4*)(base + off + bj * HALF + 4); }
;                     else { const u32x4 w = *(const u32x4*)(baseb + off + bj * HALF);
;                         b0 = (f32x4){__uint_as_float(w.x << 16), __uint_as_float(w.x & 0xffff0000u), __uint_as_float(w.y << 16), __uint_as_float(w.y & 0xffff0000u)};
;                         b1 = (f32x4){__uint_as_float(w.z << 16), __uint_as_float(w.z & 0xffff0000u), __uint_as_float(w.w << 16), __uint_as_float(w.w & 0xffff0000u)}; }
;                     acc[ai][bj][m][0] = acc[ai][bj][m][0] * s + b0 * alpha; acc[ai][bj][m][1] = acc[ai][bj][m][1] * s + b1 * alpha; }
	v_lshlrev_b32_e32 v144, 16, v224
	v_and_b32_e32 v145, 0xffff0000, v224
	v_lshlrev_b32_e32 v134, 16, v225
	v_and_b32_e32 v135, 0xffff0000, v225
	v_lshlrev_b32_e32 v152, 16, v226
	v_and_b32_e32 v153, 0xffff0000, v226
	v_lshlrev_b32_e32 v136, 16, v227
	v_and_b32_e32 v137, 0xffff0000, v227
	s_waitcnt vmcnt(2)
	v_lshlrev_b32_e32 v154, 16, v228
	v_and_b32_e32 v155, 0xffff0000, v228
	v_lshlrev_b32_e32 v138, 16, v229
	v_and_b32_e32 v139, 0xffff0000, v229
	v_lshlrev_b32_e32 v156, 16, v230
	v_and_b32_e32 v157, 0xffff0000, v230
	v_lshlrev_b32_e32 v140, 16, v231
	v_and_b32_e32 v141, 0xffff0000, v231
	v_pk_fma_f32 v[32:33], v[134:135], s[0:1], v[32:33] op_sel_hi:[1,0,1]
	v_pk_fma_f32 v[30:31], v[144:145], s[0:1], v[30:31] op_sel_hi:[1,0,1]
	v_pk_fma_f32 v[28:29], v[136:137], s[0:1], v[28:29] op_sel_hi:[1,0,1]
	v_pk_fma_f32 v[26:27], v[152:153], s[0:1], v[26:27] op_sel_hi:[1,0,1]
	v_pk_fma_f32 v[24:25], v[138:139], s[0:1], v[24:25] op_sel_hi:[1,0,1]
	v_pk_fma_f32 v[22:23], v[154:155], s[0:1], v[22:23] op_sel_hi:[1,0,1]
	v_pk_fma_f32 v[20:21], v[140:141], s[0:1], v[20:21] op_sel_hi:[1,0,1]
	v_pk_fma_f32 v[18:19], v[156:157], s[0:1], v[18:19] op_sel_hi:[1,0,1]
	v_mov_b32_e32 v134, v103
	v_mov_b32_e32 v135, v104
	v_mov_b32_e32 v136, v102
	v_mov_b32_e32 v137, v105
	v_pk_add_f32 v[134:135], v[134:135], v[136:137]
	v_add_f32_e32 v153, v90, v91
	v_pk_add_f32 v[134:135], v[134:135], v[134:135] op_sel_hi:[0,1]
	v_add_f32_e32 v155, v92, v93
	v_mov_b32_e32 v152, v74
	v_mov_b32_e32 v154, v75
	v_mov_b32_e32 v156, v77
	v_add_f32_e32 v157, 0, v146
	v_mov_b32_e32 v134, v76
	v_pk_add_f32 v[136:137], v[152:153], v[154:155]
	v_pk_add_f32 v[134:135], v[134:135], v[156:157]
	s_nop 0
	v_pk_add_f32 v[134:135], v[136:137], v[134:135]
	v_xor_b32_e32 v136, 32, v133
	v_add_f32_e32 v134, v134, v135
	ds_bpermute_b32 v135, v132, v134
	v_cmp_lt_i32_e32 vcc, v136, v158
	s_waitcnt lgkmcnt(0)
	v_add_f32_e32 v134, v134, v135
	v_cndmask_b32_e32 v133, v133, v136, vcc
	v_lshlrev_b32_e32 v133, 2, v133
	ds_bpermute_b32 v135, v133, v134
	s_waitcnt lgkmcnt(0)
	v_add_f32_e32 v135, v134, v135
	v_fmamk_f32 v136, v135, 0xbc800000, v97
	v_fmamk_f32 v146, v135, 0xbc800000, v95
	v_fmamk_f32 v148, v135, 0xbc800000, v105
	v_fmamk_f32 v152, v135, 0xbc800000, v103
	v_fmamk_f32 v134, v135, 0xbc800000, v96
	v_fmamk_f32 v137, v135, 0xbc800000, v94
	v_fmamk_f32 v147, v135, 0xbc800000, v104
	v_fmamk_f32 v149, v135, 0xbc800000, v102
	v_fmamk_f32 v154, v135, 0xbc800000, v93
	v_fmamk_f32 v156, v135, 0xbc800000, v91
	v_mul_f32_e32 v146, v146, v146
	v_mul_f32_e32 v136, v136, v136
	v_mul_f32_e32 v152, v152, v152
	v_mul_f32_e32 v148, v148, v148
	v_fmamk_f32 v153, v135, 0xbc800000, v92
	v_fmamk_f32 v155, v135, 0xbc800000, v90
	v_fmamk_f32 v158, v135, 0xbc800000, v77
	v_fmamk_f32 v160, v135, 0xbc800000, v75
	v_mul_f32_e32 v156, v156, v156
	v_mul_f32_e32 v154, v154, v154
	v_fmac_f32_e32 v146, v137, v137
	v_fmac_f32_e32 v136, v134, v134
	v_fmac_f32_e32 v152, v149, v149
	v_fmac_f32_e32 v148, v147, v147
	v_fmamk_f32 v157, v135, 0xbc800000, v76
	v_fmamk_f32 v159, v135, 0xbc800000, v74
	v_mul_f32_e32 v160, v160, v160
	v_mul_f32_e32 v158, v158, v158
	v_fmac_f32_e32 v156, v155, v155
	v_fmac_f32_e32 v154, v153, v153
	v_add_f32_e32 v134, v146, v136
	v_add_f32_e32 v136, v152, v148
	v_fmac_f32_e32 v160, v159, v159
	v_fmac_f32_e32 v158, v157, v157
	v_add_f32_e32 v137, v156, v154
	v_add_f32_e32 v134, v134, v136
	v_add_f32_e32 v146, v160, v158
	v_add_f32_e32 v134, v137, v134
	v_add_f32_e32 v136, v146, v134
	ds_bpermute_b32 v137, v132, v136
	v_and_b32_e32 v134, 63, v150
	v_cmp_gt_u32_e32 vcc, 16, v134
	s_waitcnt lgkmcnt(0)
	v_add_f32_e32 v136, v136, v137
	ds_bpermute_b32 v137, v133, v136
	s_waitcnt vmcnt(1)
	v_lshlrev_b32_e32 v146, 16, v232
	v_and_b32_e32 v147, 0xffff0000, v232
	v_lshlrev_b32_e32 v138, 16, v233
	v_and_b32_e32 v139, 0xffff0000, v233
	v_lshlrev_b32_e32 v148, 16, v234
	v_and_b32_e32 v149, 0xffff0000, v234
	v_lshlrev_b32_e32 v140, 16, v235
	v_and_b32_e32 v141, 0xffff0000, v235
	s_waitcnt vmcnt(0)
	v_lshlrev_b32_e32 v152, 16, v236
	v_and_b32_e32 v153, 0xffff0000, v236
	v_lshlrev_b32_e32 v142, 16, v237
	v_and_b32_e32 v143, 0xffff0000, v237
	v_lshlrev_b32_e32 v154, 16, v238
	v_and_b32_e32 v155, 0xffff0000, v238
	v_lshlrev_b32_e32 v144, 16, v239
	v_and_b32_e32 v145, 0xffff0000, v239
	v_pk_fma_f32 v[16:17], v[138:139], s[0:1], v[16:17] op_sel_hi:[1,0,1]
	v_pk_fma_f32 v[14:15], v[146:147], s[0:1], v[14:15] op_sel_hi:[1,0,1]
	v_pk_fma_f32 v[12:13], v[140:141], s[0:1], v[12:13] op_sel_hi:[1,0,1]
	v_pk_fma_f32 v[10:11], v[148:149], s[0:1], v[10:11] op_sel_hi:[1,0,1]
	v_pk_fma_f32 v[8:9], v[142:143], s[0:1], v[8:9] op_sel_hi:[1,0,1]
	v_pk_fma_f32 v[6:7], v[152:153], s[0:1], v[6:7] op_sel_hi:[1,0,1]
	v_pk_fma_f32 v[4:5], v[144:145], s[0:1], v[4:5] op_sel_hi:[1,0,1]
	v_pk_fma_f32 v[2:3], v[154:155], s[0:1], v[2:3] op_sel_hi:[1,0,1]
	s_lshl_b32 s0, s13, 3
	s_add_i32 s2, s0, 0
	s_and_saveexec_b64 s[0:1], vcc
	s_cbranch_execz .LBB0_1498
	s_lshl_b32 s3, s17, 11
	s_add_i32 s3, s2, s3
	v_mul_f32_e32 v138, 0x3c800000, v135
	v_lshl_add_u32 v135, v151, 5, s3
	s_waitcnt lgkmcnt(0)
	v_add_f32_e32 v139, v136, v137
	ds_write_b64 v135, v[138:139]

;     __device__ __forceinline__ void fused(f32x4 (&acc)[2][2][4][2], const Unit& u, int wr, int wc, int fr, int fq, PG8_LAS unsigned char* lds, int wid, int lane) const {
;     ...
;             for (int m = 0; m < 4; ++m) { const size_t off = (size_t)(u.pm * BM + ai * HALF + wr * 64 + m * 16 + fr) * ldc + col0;
; #pragma unroll
;                 for (int bj = 0; bj < 2; ++bj) { f32x4 b0, b1;
;                     if (base) { b0 = *(const f32x4*)(base + off + bj * HALF); b1 = *(const f32x4*)(base + off + bj * HALF + 4); }
;                     else { const u32x4 w = *(const u32x4*)(baseb + off + bj * HALF);
;                         b0 = (f32x4){__uint_as_float(w.x << 16), __uint_as_float(w.x & 0xffff0000u), __uint_as_float(w.y << 16), __uint_as_float(w.y & 0xffff0000u)};
;                         b1 = (f32x4){__uint_as_float(w.z << 16), __uint_as_float(w.z & 0xffff0000u), __uint_as_float(w.w << 16), __uint_as_float(w.w & 0xffff0000u)}; }
;                     acc[ai][bj][m][0] = acc[ai][bj][m][0] * s + b0 * alpha; acc[ai][bj][m][1] = acc[ai][bj][m][1] * s + b1 * alpha; }
.LBB0_1713:
	s_lshl_b32 s0, s27, 5
	s_lshl_b32 s1, s12, 8
	v_lshrrev_b32_e32 v130, 1, v150
	s_or_b32 s0, s1, s0
	s_lshl_b32 s18, s25, 8
	v_and_or_b32 v130, v130, 24, s0
	s_add_i32 s0, s18, s35
	v_or_b32_e32 v132, s0, v151
	v_ashrrev_i32_e32 v133, 31, v132
	v_ashrrev_i32_e32 v131, 31, v130
	v_lshlrev_b64 v[134:135], 11, v[132:133]
	v_lshl_add_u64 v[136:137], s[10:11], 0, v[134:135]
	v_lshlrev_b64 v[134:135], 1, v[130:131]
	v_lshl_add_u64 v[140:141], v[136:137], 0, v[134:135]
	s_barrier
	s_nop 1
	v_subrev_u32_e32 v175, s10, v140
	global_load_dwordx4 v[176:179], v175, s[10:11]
	global_load_dwordx4 v[180:183], v175, s[10:11] offset:256
	s_add_u32 s100, s10, 0x8000
	s_addc_u32 s101, s11, 0
	global_load_dwordx4 v[184:187], v175, s[100:101]
	global_load_dwordx4 v[188:191], v175, s[100:101] offset:256
	s_add_u32 s98, s10, 0x10000
	s_addc_u32 s99, s11, 0
	global_load_dwordx4 v[192:195], v175, s[98:99]
	global_load_dwordx4 v[196:199], v175, s[98:99] offset:256
	s_add_u32 s100, s10, 0x18000
	s_addc_u32 s101, s11, 0
	global_load_dwordx4 v[200:203], v175, s[100:101]
	global_load_dwordx4 v[204:207], v175, s[100:101] offset:256
	s_add_u32 s98, s10, 0x40000
	s_addc_u32 s99, s11, 0
	global_load_dwordx4 v[208:211], v175, s[98:99]
	global_load_dwordx4 v[212:215], v175, s[98:99] offset:256
	s_add_u32 s100, s10, 0x48000
	s_addc_u32 s101, s11, 0
	global_load_dwordx4 v[216:219], v175, s[100:101]
	global_load_dwordx4 v[220:223], v175, s[100:101] offset:256
	s_add_u32 s98, s10, 0x50000
	s_addc_u32 s99, s11, 0
	global_load_dwordx4 v[224:227], v175, s[98:99]
	global_load_dwordx4 v[228:231], v175, s[98:99] offset:256
	s_add_u32 s100, s10, 0x58000
	s_addc_u32 s101, s11, 0
	global_load_dwordx4 v[232:235], v175, s[100:101]
	global_load_dwordx4 v[236:239], v175, s[100:101] offset:256
	s_nop 0
	v_or_b32_e32 v144, 16, v132
	v_ashrrev_i32_e32 v145, 31, v144
	s_mov_b32 s0, 0x3f9837f0
	v_lshlrev_b64 v[144:145], 11, v[144:145]
	v_lshl_add_u64 v[144:145], s[10:11], 0, v[144:145]
	v_lshl_add_u64 v[144:145], v[144:145], 0, v[134:135]
	v_mbcnt_hi_u32_b32 v156, -1, v1
	v_and_b32_e32 v133, 64, v156
	v_add_u32_e32 v157, 64, v133
	v_xor_b32_e32 v1, 16, v156
	v_cmp_lt_i32_e32 vcc, v1, v157
	s_waitcnt vmcnt(14)
	v_lshlrev_b32_e32 v146, 16, v176
	v_and_b32_e32 v147, 0xffff0000, v176
	v_lshlrev_b32_e32 v136, 16, v177
	v_and_b32_e32 v137, 0xffff0000, v177
	v_lshlrev_b32_e32 v148, 16, v178
	v_and_b32_e32 v149, 0xffff0000, v178
	v_lshlrev_b32_e32 v138, 16, v179
	v_and_b32_e32 v139, 0xffff0000, v179
	v_lshlrev_b32_e32 v152, 16, v180
	v_and_b32_e32 v153, 0xffff0000, v180
	v_lshlrev_b32_e32 v140, 16, v181
	v_and_b32_e32 v141, 0xffff0000, v181
	v_lshlrev_b32_e32 v154, 16, v182
	v_and_b32_e32 v155, 0xffff0000, v182
	v_lshlrev_b32_e32 v142, 16, v183
	v_and_b32_e32 v143, 0xffff0000, v183
	v_pk_mul_f32 v[146:147], v[146:147], s[0:1] op_sel_hi:[1,0]
	v_pk_mul_f32 v[136:137], v[136:137], s[0:1] op_sel_hi:[1,0]
	v_pk_mul_f32 v[148:149], v[148:149], s[0:1] op_sel_hi:[1,0]
	v_pk_mul_f32 v[138:139], v[138:139], s[0:1] op_sel_hi:[1,0]
	v_pk_mul_f32 v[152:153], v[152:153], s[0:1] op_sel_hi:[1,0]
	v_pk_mul_f32 v[140:141], v[140:141], s[0:1] op_sel_hi:[1,0]
	v_pk_mul_f32 v[154:155], v[154:155], s[0:1] op_sel_hi:[1,0]
	v_pk_mul_f32 v[142:143], v[142:143], s[0:1] op_sel_hi:[1,0]
	v_pk_fma_f32 v[72:73], v[72:73], 0.5, v[136:137] op_sel_hi:[1,0,1]
	v_pk_fma_f32 v[70:71], v[70:71], 0.5, v[146:147] op_sel_hi:[1,0,1]
	v_pk_fma_f32 v[80:81], v[80:81], 0.5, v[138:139] op_sel_hi:[1,0,1]
	v_pk_fma_f32 v[78:79], v[78:79], 0.5, v[148:149] op_sel_hi:[1,0,1]
	v_pk_fma_f32 v[68:69], v[68:69], 0.5, v[140:141] op_sel_hi:[1,0,1]
	v_pk_fma_f32 v[66:67], v[66:67], 0.5, v[152:153] op_sel_hi:[1,0,1]
	v_pk_fma_f32 v[76:77], v[76:77], 0.5, v[142:143] op_sel_hi:[1,0,1]
	v_pk_fma_f32 v[74:75], v[74:75], 0.5, v[154:155] op_sel_hi:[1,0,1]
	v_cndmask_b32_e32 v1, v156, v1, vcc
	v_or_b32_e32 v144, 32, v132
	v_ashrrev_i32_e32 v145, 31, v144
	v_lshlrev_b64 v[144:145], 11, v[144:145]
	v_lshl_add_u64 v[144:145], s[10:11], 0, v[144:145]
	v_lshl_add_u64 v[144:145], v[144:145], 0, v[134:135]
	v_lshlrev_b32_e32 v1, 2, v1
	s_waitcnt vmcnt(13)
	v_lshlrev_b32_e32 v146, 16, v184
	v_and_b32_e32 v147, 0xffff0000, v184
	v_lshlrev_b32_e32 v136, 16, v185
	v_and_b32_e32 v137, 0xffff0000, v185
	v_lshlrev_b32_e32 v148, 16, v186
	v_and_b32_e32 v149, 0xffff0000, v186
	v_lshlrev_b32_e32 v138, 16, v187
	v_and_b32_e32 v139, 0xffff0000, v187
	s_waitcnt vmcnt(12)
	v_lshlrev_b32_e32 v152, 16, v188
	v_and_b32_e32 v153, 0xffff0000, v188
	v_lshlrev_b32_e32 v140, 16, v189
	v_and_b32_e32 v141, 0xffff0000, v189
	v_lshlrev_b32_e32 v154, 16, v190
	v_and_b32_e32 v155, 0xffff0000, v190
	v_lshlrev_b32_e32 v142, 16, v191
	v_and_b32_e32 v143, 0xffff0000, v191
	v_pk_mul_f32 v[146:147], v[146:147], s[0:1] op_sel_hi:[1,0]
	v_pk_mul_f32 v[136:137], v[136:137], s[0:1] op_sel_hi:[1,0]
	v_pk_mul_f32 v[148:149], v[148:149], s[0:1] op_sel_hi:[1,0]
	v_pk_mul_f32 v[138:139], v[138:139], s[0:1] op_sel_hi:[1,0]
	v_pk_mul_f32 v[152:153], v[152:153], s[0:1] op_sel_hi:[1,0]
	v_pk_mul_f32 v[140:141], v[140:141], s[0:1] op_sel_hi:[1,0]
	v_pk_mul_f32 v[154:155], v[154:155], s[0:1] op_sel_hi:[1,0]
	v_pk_mul_f32 v[142:143], v[142:143], s[0:1] op_sel_hi:[1,0]
	v_pk_fma_f32 v[96:97], v[96:97], 0.5, v[136:137] op_sel_hi:[1,0,1]
	v_pk_fma_f32 v[94:95], v[94:95], 0.5, v[146:147] op_sel_hi:[1,0,1]
	v_pk_fma_f32 v[120:121], v[120:121], 0.5, v[138:139] op_sel_hi:[1,0,1]
	v_pk_fma_f32 v[118:119], v[118:119], 0.5, v[148:149] op_sel_hi:[1,0,1]
	v_pk_fma_f32 v[84:85], v[84:85], 0.5, v[140:141] op_sel_hi:[1,0,1]
	v_pk_fma_f32 v[82:83], v[82:83], 0.5, v[152:153] op_sel_hi:[1,0,1]
	v_pk_fma_f32 v[88:89], v[88:89], 0.5, v[142:143] op_sel_hi:[1,0,1]
	v_pk_fma_f32 v[86:87], v[86:87], 0.5, v[154:155] op_sel_hi:[1,0,1]
	s_nop 0
	v_or_b32_e32 v144, 48, v132
	v_ashrrev_i32_e32 v145, 31, v144
	v_lshlrev_b64 v[144:145], 11, v[144:145]
	v_lshl_add_u64 v[144:145], s[10:11], 0, v[144:145]
	v_lshl_add_u64 v[144:145], v[144:145], 0, v[134:135]
	s_waitcnt vmcnt(11)
;     __device__ __forceinline__ void fused(f32x4 (&acc)[2][2][4][2], const Unit& u, int wr, int wc, int fr, int fq, PG8_LAS unsigned char* lds, int wid, int lane) const {
;     ...
;             for (int m = 0; m < 4; ++m) { const size_t off = (size_t)(u.pm * BM + ai * HALF + wr * 64 + m * 16 + fr) * ldc + col0;
; #pragma unroll
;                 for (int bj = 0; bj < 2; ++bj) { f32x4 b0, b1;
;                     if (base) { b0 = *(const f32x4*)(base + off + bj * HALF); b1 = *(const f32x4*)(base + off + bj * HALF + 4); }
;                     else { const u32x4 w = *(const u32x4*)(baseb + off + bj * HALF);
;                         b0 = (f32x4){__uint_as_float(w.x << 16), __uint_as_float(w.x & 0xffff0000u), __uint_as_float(w.y << 16), __uint_as_float(w.y & 0xffff0000u)};
;                         b1 = (f32x4){__uint_as_float(w.z << 16), __uint_as_float(w.z & 0xffff0000u), __uint_as_float(w.w << 16), __uint_as_float(w.w & 0xffff0000u)}; }
;                     acc[ai][bj][m][0] = acc[ai][bj][m][0] * s + b0 * alpha; acc[ai][bj][m][1] = acc[ai][bj][m][1] * s + b1 * alpha; }
	v_lshlrev_b32_e32 v146, 16, v192
	v_and_b32_e32 v147, 0xffff0000, v192
	v_lshlrev_b32_e32 v136, 16, v193
	v_and_b32_e32 v137, 0xffff0000, v193
	v_lshlrev_b32_e32 v148, 16, v194
	v_and_b32_e32 v149, 0xffff0000, v194
	v_lshlrev_b32_e32 v138, 16, v195
	v_and_b32_e32 v139, 0xffff0000, v195
	s_waitcnt vmcnt(10)
	v_lshlrev_b32_e32 v152, 16, v196
	v_and_b32_e32 v153, 0xffff0000, v196
	v_lshlrev_b32_e32 v140, 16, v197
	v_and_b32_e32 v141, 0xffff0000, v197
	v_lshlrev_b32_e32 v154, 16, v198
	v_and_b32_e32 v155, 0xffff0000, v198
	v_lshlrev_b32_e32 v142, 16, v199
	v_and_b32_e32 v143, 0xffff0000, v199
	v_pk_mul_f32 v[146:147], v[146:147], s[0:1] op_sel_hi:[1,0]
	v_pk_mul_f32 v[136:137], v[136:137], s[0:1] op_sel_hi:[1,0]
	v_pk_mul_f32 v[148:149], v[148:149], s[0:1] op_sel_hi:[1,0]
	v_pk_mul_f32 v[138:139], v[138:139], s[0:1] op_sel_hi:[1,0]
	v_pk_mul_f32 v[152:153], v[152:153], s[0:1] op_sel_hi:[1,0]
	v_pk_mul_f32 v[140:141], v[140:141], s[0:1] op_sel_hi:[1,0]
	v_pk_mul_f32 v[154:155], v[154:155], s[0:1] op_sel_hi:[1,0]
	v_pk_mul_f32 v[142:143], v[142:143], s[0:1] op_sel_hi:[1,0]
	v_pk_fma_f32 v[108:109], v[108:109], 0.5, v[136:137] op_sel_hi:[1,0,1]
	v_pk_fma_f32 v[106:107], v[106:107], 0.5, v[146:147] op_sel_hi:[1,0,1]
	v_pk_fma_f32 v[116:117], v[116:117], 0.5, v[138:139] op_sel_hi:[1,0,1]
	v_pk_fma_f32 v[114:115], v[114:115], 0.5, v[148:149] op_sel_hi:[1,0,1]
	v_pk_fma_f32 v[92:93], v[92:93], 0.5, v[140:141] op_sel_hi:[1,0,1]
	v_pk_fma_f32 v[90:91], v[90:91], 0.5, v[152:153] op_sel_hi:[1,0,1]
	v_pk_fma_f32 v[100:101], v[100:101], 0.5, v[142:143] op_sel_hi:[1,0,1]
	v_pk_fma_f32 v[98:99], v[98:99], 0.5, v[154:155] op_sel_hi:[1,0,1]
	s_nop 0
	v_add_u32_e32 v144, 0x80, v132
	v_ashrrev_i32_e32 v145, 31, v144
	v_lshlrev_b64 v[144:145], 11, v[144:145]
	v_lshl_add_u64 v[144:145], s[10:11], 0, v[144:145]
	v_lshl_add_u64 v[144:145], v[144:145], 0, v[134:135]
	s_waitcnt vmcnt(9)
	v_lshlrev_b32_e32 v146, 16, v200
	v_and_b32_e32 v147, 0xffff0000, v200
	v_lshlrev_b32_e32 v136, 16, v201
	v_and_b32_e32 v137, 0xffff0000, v201
	v_lshlrev_b32_e32 v148, 16, v202
	v_and_b32_e32 v149, 0xffff0000, v202
	v_lshlrev_b32_e32 v138, 16, v203
	v_and_b32_e32 v139, 0xffff0000, v203
	s_waitcnt vmcnt(8)
	v_lshlrev_b32_e32 v152, 16, v204
	v_and_b32_e32 v153, 0xffff0000, v204
	v_lshlrev_b32_e32 v140, 16, v205
	v_and_b32_e32 v141, 0xffff0000, v205
	v_lshlrev_b32_e32 v154, 16, v206
	v_and_b32_e32 v155, 0xffff0000, v206
	v_lshlrev_b32_e32 v142, 16, v207
	v_and_b32_e32 v143, 0xffff0000, v207
	v_pk_mul_f32 v[146:147], v[146:147], s[0:1] op_sel_hi:[1,0]
	v_pk_mul_f32 v[136:137], v[136:137], s[0:1] op_sel_hi:[1,0]
	v_pk_mul_f32 v[148:149], v[148:149], s[0:1] op_sel_hi:[1,0]
	v_pk_mul_f32 v[138:139], v[138:139], s[0:1] op_sel_hi:[1,0]
	v_pk_mul_f32 v[152:153], v[152:153], s[0:1] op_sel_hi:[1,0]
	v_pk_mul_f32 v[140:141], v[140:141], s[0:1] op_sel_hi:[1,0]
	v_pk_mul_f32 v[154:155], v[154:155], s[0:1] op_sel_hi:[1,0]
	v_pk_mul_f32 v[142:143], v[142:143], s[0:1] op_sel_hi:[1,0]
	v_pk_fma_f32 v[124:125], v[124:125], 0.5, v[136:137] op_sel_hi:[1,0,1]
	v_pk_fma_f32 v[122:123], v[122:123], 0.5, v[146:147] op_sel_hi:[1,0,1]
	v_pk_fma_f32 v[128:129], v[128:129], 0.5, v[138:139] op_sel_hi:[1,0,1]
	v_pk_fma_f32 v[126:127], v[126:127], 0.5, v[148:149] op_sel_hi:[1,0,1]
	v_pk_fma_f32 v[104:105], v[104:105], 0.5, v[140:141] op_sel_hi:[1,0,1]
	v_pk_fma_f32 v[102:103], v[102:103], 0.5, v[152:153] op_sel_hi:[1,0,1]
	v_pk_fma_f32 v[112:113], v[112:113], 0.5, v[142:143] op_sel_hi:[1,0,1]
	v_pk_fma_f32 v[110:111], v[110:111], 0.5, v[154:155] op_sel_hi:[1,0,1]
	s_nop 0
	v_add_u32_e32 v144, 0x90, v132
	v_ashrrev_i32_e32 v145, 31, v144
	v_lshlrev_b64 v[144:145], 11, v[144:145]
	v_lshl_add_u64 v[144:145], s[10:11], 0, v[144:145]
	v_lshl_add_u64 v[144:145], v[144:145], 0, v[134:135]
	s_waitcnt vmcnt(7)
	v_lshlrev_b32_e32 v146, 16, v208
	v_and_b32_e32 v147, 0xffff0000, v208
	v_lshlrev_b32_e32 v136, 16, v209
	v_and_b32_e32 v137, 0xffff0000, v209
	v_lshlrev_b32_e32 v148, 16, v210
	v_and_b32_e32 v149, 0xffff0000, v210
	v_lshlrev_b32_e32 v138, 16, v211
	v_and_b32_e32 v139, 0xffff0000, v211
	s_waitcnt vmcnt(6)
	v_lshlrev_b32_e32 v152, 16, v212
	v_and_b32_e32 v153, 0xffff0000, v212
	v_lshlrev_b32_e32 v140, 16, v213
	v_and_b32_e32 v141, 0xffff0000, v213
	v_lshlrev_b32_e32 v154, 16, v214
	v_and_b32_e32 v155, 0xffff0000, v214
	v_lshlrev_b32_e32 v142, 16, v215
	v_and_b32_e32 v143, 0xffff0000, v215
	v_pk_mul_f32 v[146:147], v[146:147], s[0:1] op_sel_hi:[1,0]
	v_pk_mul_f32 v[136:137], v[136:137], s[0:1] op_sel_hi:[1,0]
	v_pk_mul_f32 v[148:149], v[148:149], s[0:1] op_sel_hi:[1,0]
	v_pk_mul_f32 v[138:139], v[138:139], s[0:1] op_sel_hi:[1,0]
	v_pk_mul_f32 v[152:153], v[152:153], s[0:1] op_sel_hi:[1,0]
	v_pk_mul_f32 v[140:141], v[140:141], s[0:1] op_sel_hi:[1,0]
	v_pk_mul_f32 v[154:155], v[154:155], s[0:1] op_sel_hi:[1,0]
	v_pk_mul_f32 v[142:143], v[142:143], s[0:1] op_sel_hi:[1,0]
	v_pk_fma_f32 v[64:65], v[64:65], 0.5, v[136:137] op_sel_hi:[1,0,1]
	v_pk_fma_f32 v[62:63], v[62:63], 0.5, v[146:147] op_sel_hi:[1,0,1]
	v_pk_fma_f32 v[60:61], v[60:61], 0.5, v[138:139] op_sel_hi:[1,0,1]
	v_pk_fma_f32 v[58:59], v[58:59], 0.5, v[148:149] op_sel_hi:[1,0,1]
	v_pk_fma_f32 v[56:57], v[56:57], 0.5, v[140:141] op_sel_hi:[1,0,1]
	v_pk_fma_f32 v[54:55], v[54:55], 0.5, v[152:153] op_sel_hi:[1,0,1]
	v_pk_fma_f32 v[52:53], v[52:53], 0.5, v[142:143] op_sel_hi:[1,0,1]
	v_pk_fma_f32 v[50:51], v[50:51], 0.5, v[154:155] op_sel_hi:[1,0,1]
	s_nop 0
	v_add_u32_e32 v144, 0xa0, v132
	v_ashrrev_i32_e32 v145, 31, v144
	v_lshlrev_b64 v[144:145], 11, v[144:145]
	v_lshl_add_u64 v[144:145], s[10:11], 0, v[144:145]
	v_lshl_add_u64 v[144:145], v[144:145], 0, v[134:135]
	v_add_u32_e32 v132, 0xb0, v132
	v_ashrrev_i32_e32 v133, 31, v132
	v_lshlrev_b64 v[132:133], 11, v[132:133]
	v_lshl_add_u64 v[132:133], s[10:11], 0, v[132:133]
	v_lshl_add_u64 v[132:133], v[132:133], 0, v[134:135]
	v_mov_b32_e32 v134, v71
	v_mov_b32_e32 v135, v72
	s_waitcnt vmcnt(5)
;     __device__ __forceinline__ bool run(const f32x4 (&v)[2][2][4][2], const Unit& u, int wr, int wc, int fr, int fq, PG8_LAS unsigned char* lds, int wid, int lane) const {
;     ...
;                 float s = 0.f;
; #pragma unroll
;                 for (int bj = 0; bj < 2; ++bj)
; #pragma unroll
;                     for (int n = 0; n < 2; ++n) { const f32x4 x = v[ai][bj][m][n]; s += (x[0] + x[1]) + (x[2] + x[3]); }
;                 s += __shfl_xor(s, 16); s += __shfl_xor(s, 32);
;     __device__ __forceinline__ void fused(f32x4 (&acc)[2][2][4][2], const Unit& u, int wr, int wc, int fr, int fq, PG8_LAS unsigned char* lds, int wid, int lane) const {
;     ...
;             for (int m = 0; m < 4; ++m) { const size_t off = (size_t)(u.pm * BM + ai * HALF + wr * 64 + m * 16 + fr) * ldc + col0;
; #pragma unroll
;                 for (int bj = 0; bj < 2; ++bj) { f32x4 b0, b1;
;                     if (base) { b0 = *(const f32x4*)(base + off + bj * HALF); b1 = *(const f32x4*)(base + off + bj * HALF + 4); }
;                     else { const u32x4 w = *(const u32x4*)(baseb + off + bj * HALF);
;                         b0 = (f32x4){__uint_as_float(w.x << 16), __uint_as_float(w.x & 0xffff0000u), __uint_as_float(w.y << 16), __uint_as_float(w.y & 0xffff0000u)};
;                         b1 = (f32x4){__uint_as_float(w.z << 16), __uint_as_float(w.z & 0xffff0000u), __uint_as_float(w.w << 16), __uint_as_float(w.w & 0xffff0000u)}; }
;                     acc[ai][bj][m][0] = acc[ai][bj][m][0] * s + b0 * alpha; acc[ai][bj][m][1] = acc[ai][bj][m][1] * s + b1 * alpha; }
	v_lshlrev_b32_e32 v146, 16, v216
	v_and_b32_e32 v147, 0xffff0000, v216
	v_lshlrev_b32_e32 v136, 16, v217
	v_and_b32_e32 v137, 0xffff0000, v217
	v_lshlrev_b32_e32 v148, 16, v218
	v_and_b32_e32 v149, 0xffff0000, v218
	v_lshlrev_b32_e32 v138, 16, v219
	v_and_b32_e32 v139, 0xffff0000, v219
	s_waitcnt vmcnt(4)
	v_lshlrev_b32_e32 v152, 16, v220
	v_and_b32_e32 v153, 0xffff0000, v220
	v_lshlrev_b32_e32 v140, 16, v221
	v_and_b32_e32 v141, 0xffff0000, v221
	v_lshlrev_b32_e32 v154, 16, v222
	v_and_b32_e32 v155, 0xffff0000, v222
	v_lshlrev_b32_e32 v142, 16, v223
	v_and_b32_e32 v143, 0xffff0000, v223
	v_pk_mul_f32 v[146:147], v[146:147], s[0:1] op_sel_hi:[1,0]
	v_pk_mul_f32 v[136:137], v[136:137], s[0:1] op_sel_hi:[1,0]
	v_pk_mul_f32 v[148:149], v[148:149], s[0:1] op_sel_hi:[1,0]
	v_pk_mul_f32 v[138:139], v[138:139], s[0:1] op_sel_hi:[1,0]
	v_pk_mul_f32 v[152:153], v[152:153], s[0:1] op_sel_hi:[1,0]
	v_pk_mul_f32 v[140:141], v[140:141], s[0:1] op_sel_hi:[1,0]
	v_pk_mul_f32 v[154:155], v[154:155], s[0:1] op_sel_hi:[1,0]
	v_pk_mul_f32 v[142:143], v[142:143], s[0:1] op_sel_hi:[1,0]
	v_pk_fma_f32 v[48:49], v[48:49], 0.5, v[136:137] op_sel_hi:[1,0,1]
	v_pk_fma_f32 v[46:47], v[46:47], 0.5, v[146:147] op_sel_hi:[1,0,1]
	v_pk_fma_f32 v[44:45], v[44:45], 0.5, v[138:139] op_sel_hi:[1,0,1]
	v_pk_fma_f32 v[42:43], v[42:43], 0.5, v[148:149] op_sel_hi:[1,0,1]
	v_pk_fma_f32 v[40:41], v[40:41], 0.5, v[140:141] op_sel_hi:[1,0,1]
	v_pk_fma_f32 v[38:39], v[38:39], 0.5, v[152:153] op_sel_hi:[1,0,1]
	v_pk_fma_f32 v[36:37], v[36:37], 0.5, v[142:143] op_sel_hi:[1,0,1]
	v_pk_fma_f32 v[34:35], v[34:35], 0.5, v[154:155] op_sel_hi:[1,0,1]
	v_mov_b32_e32 v146, v70
	v_mov_b32_e32 v147, v73
	v_pk_add_f32 v[134:135], v[134:135], v[146:147]
	s_waitcnt vmcnt(3)
	v_lshlrev_b32_e32 v144, 16, v224
	v_and_b32_e32 v145, 0xffff0000, v224
	v_lshlrev_b32_e32 v136, 16, v225
	v_and_b32_e32 v137, 0xffff0000, v225
	v_lshlrev_b32_e32 v148, 16, v226
	v_and_b32_e32 v149, 0xffff0000, v226
	v_lshlrev_b32_e32 v138, 16, v227
	v_and_b32_e32 v139, 0xffff0000, v227
	s_waitcnt vmcnt(2)
	v_lshlrev_b32_e32 v152, 16, v228
	v_and_b32_e32 v153, 0xffff0000, v228
	v_lshlrev_b32_e32 v140, 16, v229
	v_and_b32_e32 v141, 0xffff0000, v229
	v_lshlrev_b32_e32 v154, 16, v230
	v_and_b32_e32 v155, 0xffff0000, v230
	v_lshlrev_b32_e32 v142, 16, v231
	v_and_b32_e32 v143, 0xffff0000, v231
	v_pk_mul_f32 v[144:145], v[144:145], s[0:1] op_sel_hi:[1,0]
	v_pk_mul_f32 v[136:137], v[136:137], s[0:1] op_sel_hi:[1,0]
	v_pk_mul_f32 v[148:149], v[148:149], s[0:1] op_sel_hi:[1,0]
	v_pk_mul_f32 v[138:139], v[138:139], s[0:1] op_sel_hi:[1,0]
	v_pk_mul_f32 v[152:153], v[152:153], s[0:1] op_sel_hi:[1,0]
	v_pk_mul_f32 v[140:141], v[140:141], s[0:1] op_sel_hi:[1,0]
	v_pk_mul_f32 v[154:155], v[154:155], s[0:1] op_sel_hi:[1,0]
	v_pk_mul_f32 v[142:143], v[142:143], s[0:1] op_sel_hi:[1,0]
	v_pk_fma_f32 v[32:33], v[32:33], 0.5, v[136:137] op_sel_hi:[1,0,1]
	v_pk_fma_f32 v[30:31], v[30:31], 0.5, v[144:145] op_sel_hi:[1,0,1]
	v_pk_fma_f32 v[28:29], v[28:29], 0.5, v[138:139] op_sel_hi:[1,0,1]
	v_pk_fma_f32 v[26:27], v[26:27], 0.5, v[148:149] op_sel_hi:[1,0,1]
	v_pk_fma_f32 v[24:25], v[24:25], 0.5, v[140:141] op_sel_hi:[1,0,1]
	v_pk_fma_f32 v[22:23], v[22:23], 0.5, v[152:153] op_sel_hi:[1,0,1]
	v_pk_fma_f32 v[20:21], v[20:21], 0.5, v[142:143] op_sel_hi:[1,0,1]
	v_pk_fma_f32 v[18:19], v[18:19], 0.5, v[154:155] op_sel_hi:[1,0,1]
	v_mov_b32_e32 v136, v79
	v_mov_b32_e32 v137, v80
	v_mov_b32_e32 v148, v78
	v_mov_b32_e32 v149, v81
	v_pk_add_f32 v[136:137], v[136:137], v[148:149]
	v_add_f32_e32 v133, v134, v135
	v_pk_add_f32 v[134:135], v[136:137], v[136:137] op_sel_hi:[0,1]
	v_add_f32_e32 v153, v66, v67
	v_add_f32_e32 v155, v68, v69
	v_mov_b32_e32 v152, v74
	v_mov_b32_e32 v154, v75
	v_mov_b32_e32 v132, v77
	v_add_f32_e32 v133, 0, v133
	v_mov_b32_e32 v134, v76
	v_pk_add_f32 v[146:147], v[152:153], v[154:155]
	v_pk_add_f32 v[132:133], v[134:135], v[132:133]
	s_nop 0
	v_pk_add_f32 v[132:133], v[146:147], v[132:133]
	s_nop 0
	v_add_f32_e32 v133, v132, v133
	ds_bpermute_b32 v134, v1, v133
	v_xor_b32_e32 v132, 32, v156
	v_cmp_lt_i32_e32 vcc, v132, v157
	s_waitcnt lgkmcnt(0)
;     __device__ __forceinline__ bool run(const f32x4 (&v)[2][2][4][2], const Unit& u, int wr, int wc, int fr, int fq, PG8_LAS unsigned char* lds, int wid, int lane) const {
;     ...
;                 float s = 0.f;
; #pragma unroll
;                 for (int bj = 0; bj < 2; ++bj)
; #pragma unroll
;                     for (int n = 0; n < 2; ++n) { const f32x4 x = v[ai][bj][m][n]; s += (x[0] + x[1]) + (x[2] + x[3]); }
;                 s += __shfl_xor(s, 16); s += __shfl_xor(s, 32);
;                 const float mw = s * (1.0f / 64.0f); float q = 0.f;
; #pragma unroll
;                 for (int bj = 0; bj < 2; ++bj)
; #pragma unroll
;                     for (int n = 0; n < 2; ++n) { const f32x4 d = v[ai][bj][m][n] - mw; q += (d[0] * d[0] + d[1] * d[1]) + (d[2] * d[2] + d[3] * d[3]); }
;                 q += __shfl_xor(q, 16); q += __shfl_xor(q, 32);
;                 if (fq == 0) P[(ai * HALF + wr * 64 + m * 16 + fr) * 4 + wc] = (f32x2v){mw, q};
;     __device__ __forceinline__ void fused(f32x4 (&acc)[2][2][4][2], const Unit& u, int wr, int wc, int fr, int fq, PG8_LAS unsigned char* lds, int wid, int lane) const {
;     ...
;                 for (int bj = 0; bj < 2; ++bj) { f32x4 b0, b1;
;                     if (base) { b0 = *(const f32x4*)(base + off + bj * HALF); b1 = *(const f32x4*)(base + off + bj * HALF + 4); }
;                     else { const u32x4 w = *(const u32x4*)(baseb + off + bj * HALF);
;                         b0 = (f32x4){__uint_as_float(w.x << 16), __uint_as_float(w.x & 0xffff0000u), __uint_as_float(w.y << 16), __uint_as_float(w.y & 0xffff0000u)};
;                         b1 = (f32x4){__uint_as_float(w.z << 16), __uint_as_float(w.z & 0xffff0000u), __uint_as_float(w.w << 16), __uint_as_float(w.w & 0xffff0000u)}; }
;                     acc[ai][bj][m][0] = acc[ai][bj][m][0] * s + b0 * alpha; acc[ai][bj][m][1] = acc[ai][bj][m][1] * s + b1 * alpha; }
	v_add_f32_e32 v133, v133, v134
	v_cndmask_b32_e32 v132, v156, v132, vcc
	v_lshlrev_b32_e32 v132, 2, v132
	ds_bpermute_b32 v134, v132, v133
	s_waitcnt lgkmcnt(0)
	v_add_f32_e32 v133, v133, v134
	v_fmamk_f32 v135, v133, 0xbc800000, v73
	v_fmamk_f32 v137, v133, 0xbc800000, v71
	v_fmamk_f32 v147, v133, 0xbc800000, v81
	v_fmamk_f32 v149, v133, 0xbc800000, v79
	v_fmamk_f32 v134, v133, 0xbc800000, v72
	v_fmamk_f32 v136, v133, 0xbc800000, v70
	v_fmamk_f32 v146, v133, 0xbc800000, v80
	v_fmamk_f32 v148, v133, 0xbc800000, v78
	v_fmamk_f32 v153, v133, 0xbc800000, v69
	v_fmamk_f32 v155, v133, 0xbc800000, v67
	v_mul_f32_e32 v137, v137, v137
	v_mul_f32_e32 v135, v135, v135
	v_mul_f32_e32 v149, v149, v149
	v_mul_f32_e32 v147, v147, v147
	v_fmamk_f32 v152, v133, 0xbc800000, v68
	v_fmamk_f32 v154, v133, 0xbc800000, v66
	v_fmamk_f32 v157, v133, 0xbc800000, v77
	v_fmamk_f32 v159, v133, 0xbc800000, v75
	v_mul_f32_e32 v155, v155, v155
	v_mul_f32_e32 v153, v153, v153
	v_fmac_f32_e32 v137, v136, v136
	v_fmac_f32_e32 v135, v134, v134
	v_fmac_f32_e32 v149, v148, v148
	v_fmac_f32_e32 v147, v146, v146
	v_fmamk_f32 v156, v133, 0xbc800000, v76
	v_fmamk_f32 v158, v133, 0xbc800000, v74
	v_mul_f32_e32 v159, v159, v159
	v_mul_f32_e32 v157, v157, v157
	v_fmac_f32_e32 v155, v154, v154
	v_fmac_f32_e32 v153, v152, v152
	v_add_f32_e32 v134, v137, v135
	v_add_f32_e32 v135, v149, v147
	v_fmac_f32_e32 v159, v158, v158
	v_fmac_f32_e32 v157, v156, v156
	v_add_f32_e32 v136, v155, v153
	v_add_f32_e32 v134, v134, v135
	v_add_f32_e32 v137, v159, v157
	v_add_f32_e32 v134, v136, v134
	v_add_f32_e32 v135, v137, v134
	ds_bpermute_b32 v136, v1, v135
	v_and_b32_e32 v134, 63, v150
	v_cmp_gt_u32_e32 vcc, 16, v134
	s_waitcnt lgkmcnt(0)
	v_add_f32_e32 v135, v135, v136
	s_waitcnt vmcnt(1)
	v_lshlrev_b32_e32 v146, 16, v232
	v_and_b32_e32 v147, 0xffff0000, v232
	v_lshlrev_b32_e32 v138, 16, v233
	v_and_b32_e32 v139, 0xffff0000, v233
	v_lshlrev_b32_e32 v148, 16, v234
	v_and_b32_e32 v149, 0xffff0000, v234
	v_lshlrev_b32_e32 v140, 16, v235
	v_and_b32_e32 v141, 0xffff0000, v235
	s_waitcnt vmcnt(0)
	v_lshlrev_b32_e32 v152, 16, v236
	v_and_b32_e32 v153, 0xffff0000, v236
	v_lshlrev_b32_e32 v142, 16, v237
	v_and_b32_e32 v143, 0xffff0000, v237
	v_lshlrev_b32_e32 v154, 16, v238
	v_and_b32_e32 v155, 0xffff0000, v238
	v_lshlrev_b32_e32 v144, 16, v239
	v_and_b32_e32 v145, 0xffff0000, v239
	ds_bpermute_b32 v136, v132, v135
	v_pk_mul_f32 v[146:147], v[146:147], s[0:1] op_sel_hi:[1,0]
	v_pk_mul_f32 v[138:139], v[138:139], s[0:1] op_sel_hi:[1,0]
	v_pk_mul_f32 v[148:149], v[148:149], s[0:1] op_sel_hi:[1,0]
	v_pk_mul_f32 v[140:141], v[140:141], s[0:1] op_sel_hi:[1,0]
	v_pk_mul_f32 v[152:153], v[152:153], s[0:1] op_sel_hi:[1,0]
	v_pk_mul_f32 v[142:143], v[142:143], s[0:1] op_sel_hi:[1,0]
	v_pk_mul_f32 v[154:155], v[154:155], s[0:1] op_sel_hi:[1,0]
	v_pk_mul_f32 v[144:145], v[144:145], s[0:1] op_sel_hi:[1,0]
	v_pk_fma_f32 v[16:17], v[16:17], 0.5, v[138:139] op_sel_hi:[1,0,1]
	v_pk_fma_f32 v[14:15], v[14:15], 0.5, v[146:147] op_sel_hi:[1,0,1]
	v_pk_fma_f32 v[12:13], v[12:13], 0.5, v[140:141] op_sel_hi:[1,0,1]
	v_pk_fma_f32 v[10:11], v[10:11], 0.5, v[148:149] op_sel_hi:[1,0,1]
	v_pk_fma_f32 v[8:9], v[8:9], 0.5, v[142:143] op_sel_hi:[1,0,1]
	v_pk_fma_f32 v[6:7], v[6:7], 0.5, v[152:153] op_sel_hi:[1,0,1]
	v_pk_fma_f32 v[4:5], v[4:5], 0.5, v[144:145] op_sel_hi:[1,0,1]
	v_pk_fma_f32 v[2:3], v[2:3], 0.5, v[154:155] op_sel_hi:[1,0,1]
	s_lshl_b32 s0, s27, 3
	s_add_i32 s2, s0, 0
	s_and_saveexec_b64 s[0:1], vcc
	s_cbranch_execz .LBB0_1715
	s_lshl_b32 s3, s26, 11
	s_add_i32 s3, s2, s3
	v_mul_f32_e32 v138, 0x3c800000, v133
	v_lshl_add_u32 v133, v151, 5, s3
	s_waitcnt lgkmcnt(0)
	v_add_f32_e32 v139, v135, v136
	ds_write_b64 v133, v[138:139]

; __global__ void __launch_bounds__(NWAVES * 64, 2) mega_fwd(Args args) {
;     extern __shared__ __attribute__((aligned(16))) unsigned char lds[];
	.amdhsa_kernel _Z8mega_fwd4Args
		.amdhsa_group_segment_fixed_size 0
		.amdhsa_private_segment_fixed_size 0
		.amdhsa_kernarg_size 472
		.amdhsa_user_sgpr_count 2
		.amdhsa_user_sgpr_dispatch_ptr 0
		.amdhsa_user_sgpr_queue_ptr 0
		.amdhsa_user_sgpr_kernarg_segment_ptr 1
		.amdhsa_user_sgpr_dispatch_id 0
		.amdhsa_user_sgpr_kernarg_preload_length 0
		.amdhsa_user_sgpr_kernarg_preload_offset 0
		.amdhsa_user_sgpr_private_segment_size 0
		.amdhsa_uses_dynamic_stack 0
		.amdhsa_enable_private_segment 0
		.amdhsa_system_sgpr_workgroup_id_x 1
		.amdhsa_system_sgpr_workgroup_id_y 0
		.amdhsa_system_sgpr_workgroup_id_z 0
		.amdhsa_system_sgpr_workgroup_info 0
		.amdhsa_system_vgpr_workitem_id 0
		.amdhsa_next_free_vgpr 256
		.amdhsa_next_free_sgpr 102
		.amdhsa_accum_offset 256
		.amdhsa_reserve_vcc 1
		.amdhsa_float_round_mode_32 0
		.amdhsa_float_round_mode_16_64 0
		.amdhsa_float_denorm_mode_32 3
		.amdhsa_float_denorm_mode_16_64 3
		.amdhsa_dx10_clamp 1
		.amdhsa_ieee_mode 1
		.amdhsa_fp16_overflow 0
		.amdhsa_tg_split 0
		.amdhsa_exception_fp_ieee_invalid_op 0
		.amdhsa_exception_fp_denorm_src 0
		.amdhsa_exception_fp_ieee_div_zero 0
		.amdhsa_exception_fp_ieee_overflow 0
		.amdhsa_exception_fp_ieee_underflow 0
		.amdhsa_exception_fp_ieee_inexact 0
		.amdhsa_exception_int_div_zero 0
	.end_amdhsa_kernel

; __global__ void __launch_bounds__(NWAVES * 64, 2) mega_fwd(Args args) {
;     extern __shared__ __attribute__((aligned(16))) unsigned char lds[];
amdhsa.kernels:
  - .agpr_count:     0
    .args:
      - .offset:         0
        .size:           216
        .value_kind:     by_value
      - .offset:         216
        .size:           4
        .value_kind:     hidden_block_count_x
      - .offset:         220
        .size:           4
        .value_kind:     hidden_block_count_y
      - .offset:         224
        .size:           4
        .value_kind:     hidden_block_count_z
      - .offset:         228
        .size:           2
        .value_kind:     hidden_group_size_x
      - .offset:         230
        .size:           2
        .value_kind:     hidden_group_size_y
      - .offset:         232
        .size:           2
        .value_kind:     hidden_group_size_z
      - .offset:         234
        .size:           2
        .value_kind:     hidden_remainder_x
      - .offset:         236
        .size:           2
        .value_kind:     hidden_remainder_y
      - .offset:         238
        .size:           2
        .value_kind:     hidden_remainder_z
      - .offset:         256
        .size:           8
        .value_kind:     hidden_global_offset_x
      - .offset:         264
        .size:           8
        .value_kind:     hidden_global_offset_y
      - .offset:         272
        .size:           8
        .value_kind:     hidden_global_offset_z
      - .offset:         280
        .size:           2
        .value_kind:     hidden_grid_dims
      - .offset:         336
        .size:           4
        .value_kind:     hidden_dynamic_lds_size
    .group_segment_fixed_size: 0
    .kernarg_segment_align: 8
    .kernarg_segment_size: 472
    .language:       OpenCL C
    .language_version:
      - 2
      - 0
    .max_flat_workgroup_size: 512
    .name:           _Z8mega_fwd4Args
    .private_segment_fixed_size: 0
    .sgpr_count:     108
    .sgpr_spill_count: 115
    .symbol:         _Z8mega_fwd4Args.kd
    .uniform_work_group_size: 1
    .uses_dynamic_stack: false
    .vgpr_count:     256
    .vgpr_spill_count: 0
    .wavefront_size: 64
